# section 7.5 packed-vs-scalar: v_pk_add/mul/fma_f32 split into scalar pairs in the attention loop, the SwiGLU epilogue and the S5 pass-2 loop (333 sites, bit-identical)
# speedup vs baseline: 1.0022x; 1.0022x over previous
.LBB0_185:
	v_or_b32_e32 v204, s11, v239
	v_cndmask_b32_e64 v0, 0, 1, s[6:7]
	v_ashrrev_i32_e32 v205, 31, v204
	v_cmp_ne_u32_e32 vcc, 1, v0
	v_lshlrev_b64 v[0:1], 11, v[204:205]
	v_or_b32_e32 v200, 16, v204
	v_lshl_add_u64 v[0:1], v[146:147], 0, v[0:1]
	v_ashrrev_i32_e32 v201, 31, v200
	global_load_dwordx2 v[206:207], v[0:1], off
	v_lshlrev_b64 v[0:1], 11, v[200:201]
	v_lshl_add_u64 v[0:1], v[146:147], 0, v[0:1]
	global_load_dwordx2 v[202:203], v[0:1], off
	s_waitcnt vmcnt(2)
	v_cndmask_b32_e64 v3, v107, v103, s[6:7]
	v_cndmask_b32_e64 v2, v106, v102, s[6:7]
	v_cndmask_b32_e64 v1, v105, v101, s[6:7]
	v_cndmask_b32_e64 v0, v104, v100, s[6:7]
	s_mov_b32 s11, 32
	s_and_b64 vcc, exec, vcc
	v_mfma_f32_32x32x16_bf16 v[32:47], v[0:3], v[72:75], 0
	v_mfma_f32_32x32x16_bf16 v[48:63], v[0:3], v[64:67], 0
	s_nop 10
	v_mul_f32_e64 v162, v190, v32
	v_mul_f32_e64 v163, v191, v32
	v_mov_b32_e32 v223, v34
	v_mfma_f32_32x32x16_bf16 v[16:31], v[0:3], v[68:71], 0
	v_fma_f32 v164, v126, v48, -v162
	v_fma_f32 v165, v127, v49, -v163
	v_fma_f32 v162, v126, v48, v162
	v_fma_f32 v163, v127, v48, v163
	v_mov_b32_e32 v222, v50
	v_mov_b32_e32 v165, v163
	v_mov_b32_e32 v162, v49
	v_mov_b32_e32 v163, v33
	v_add_f32_e32 v162, v162, v164
	v_add_f32_e32 v163, v163, v165
	v_mov_b32_e32 v34, v51
	v_mul_f32_e32 v208, v128, v162
	v_fma_f32 v210, v128, v162, v208
	v_fma_f32 v211, v129, v163, v208
	v_mul_f32_e32 v208, v190, v36
	v_mul_f32_e32 v209, v191, v36
	v_mul_f32_e32 v164, v127, v163
	v_fma_f32 v212, v126, v52, -v208
	v_fma_f32 v213, v127, v53, -v209
	v_fma_f32 v208, v126, v52, v208
	v_fma_f32 v209, v127, v52, v209
	v_fma_f32 v165, v127, v163, -v164
	v_fma_f32 v164, v126, v162, -v164
	v_mov_b32_e32 v213, v209
	v_mov_b32_e32 v208, v53
	v_mov_b32_e32 v209, v37
	v_add_f32_e32 v208, v208, v212
	v_add_f32_e32 v209, v209, v213
	v_mov_b32_e32 v165, v211
	v_mul_f32_e32 v210, v127, v209
	v_fma_f32 v212, v126, v208, -v210
	v_fma_f32 v213, v127, v209, -v210
	v_mul_f32_e32 v210, v128, v208
	v_add_f32_e32 v164, v222, v164
	v_add_f32_e32 v165, v223, v165
	v_fma_f32 v214, v128, v208, v210
	v_fma_f32 v215, v129, v209, v210
	v_mul_f32_e32 v210, v158, v164
	v_mul_f32_e32 v211, v159, v165
	v_mov_b32_e32 v49, v32
	v_fma_f32 v222, v156, v164, -v211
	v_fma_f32 v223, v157, v165, -v210
	v_pk_fma_f32 v[210:211], v[156:157], v[164:165], v[210:211] op_sel:[0,0,1] op_sel_hi:[1,1,0]
	v_mov_b32_e32 v213, v215
	v_mov_b32_e32 v223, v211
	v_add_f32_e32 v34, v34, v222
	v_add_f32_e32 v35, v35, v223
	ds_bpermute_b32 v37, v234, v34
	ds_bpermute_b32 v53, v234, v35
	v_mul_f32_e32 v210, v154, v196
	v_mul_f32_e32 v211, v155, v196
	v_mfma_f32_32x32x16_bf16 v[0:15], v[0:3], v[76:79], 0
	v_fma_f32 v222, v150, v198, -v210
	v_fma_f32 v223, v151, v199, -v211
	v_fma_f32 v210, v150, v198, v210
	v_fma_f32 v211, v151, v198, v211
	s_waitcnt lgkmcnt(0)
	v_cndmask_b32_e64 v51, v53, v35, s[36:37]
	v_cndmask_b32_e64 v50, v37, v34, s[36:37]
	v_mov_b32_e32 v223, v211
	v_add_f32_e32 v50, v222, v50
	v_add_f32_e32 v51, v223, v51
	s_nop 0
	v_cndmask_b32_e64 v199, v51, v196, s[36:37]
	v_cndmask_b32_e64 v198, v50, v198, s[36:37]
	v_fma_f32 v32, v156, v198, v48
	v_fma_f32 v33, v157, v199, v49
	v_mul_f32_e32 v48, v158, v198
	v_mul_f32_e32 v49, v159, v199
	s_nop 0
	v_add_f32_e64 v210, v32, -v49
	v_add_f32_e64 v211, v33, -v48
	v_add_f32_e32 v32, v32, v49
	v_add_f32_e32 v33, v33, v48
	v_mul_f32_e32 v48, v172, v198
	v_mul_f32_e32 v49, v173, v199
	v_cvt_pk_bf16_f32 v245, v210, v33
	v_fma_f32 v32, v170, v198, v162
	v_fma_f32 v33, v171, v199, v163
	s_nop 0
	v_add_f32_e64 v162, v32, -v49
	v_add_f32_e64 v163, v33, -v48
	v_add_f32_e32 v32, v32, v49
	v_add_f32_e32 v33, v33, v48
	v_mul_f32_e32 v48, v138, v198
	v_mul_f32_e32 v49, v139, v199
	v_cvt_pk_bf16_f32 v244, v162, v33
	v_fma_f32 v32, v136, v198, v164
	v_fma_f32 v33, v137, v199, v165
	s_nop 0
	v_add_f32_e64 v162, v32, -v49
	v_add_f32_e64 v163, v33, -v48
	v_add_f32_e32 v32, v32, v49
	v_add_f32_e32 v33, v33, v48
	v_mul_f32_e32 v48, v176, v198
	v_mul_f32_e32 v49, v177, v199
	v_cvt_pk_bf16_f32 v243, v162, v33
	v_fma_f32 v32, v174, v198, v34
	v_fma_f32 v33, v175, v199, v35
	v_cndmask_b32_e64 v35, v35, v53, s[36:37]
	v_add_f32_e64 v162, v32, -v49
	v_add_f32_e64 v163, v33, -v48
	v_add_f32_e32 v32, v32, v49
	v_add_f32_e32 v33, v33, v48
	v_cndmask_b32_e64 v34, v34, v37, s[36:37]
	v_cvt_pk_bf16_f32 v242, v162, v33
	v_mov_b32_e32 v32, v54
	v_mov_b32_e32 v33, v38
	v_add_f32_e32 v32, v32, v212
	v_add_f32_e32 v33, v33, v213
	v_mov_b32_e32 v38, v55
	v_mul_f32_e32 v48, v158, v32
	v_mul_f32_e32 v49, v159, v33
	v_mov_b32_e32 v53, v36
	v_fma_f32 v162, v156, v32, -v49
	v_fma_f32 v163, v157, v33, -v48
	v_pk_fma_f32 v[48:49], v[156:157], v[32:33], v[48:49] op_sel:[0,0,1] op_sel_hi:[1,1,0]
	s_nop 0
	v_mov_b32_e32 v163, v49
	v_add_f32_e32 v198, v38, v162
	v_add_f32_e32 v199, v39, v163
	v_mul_f32_e32 v48, v176, v50
	v_mul_f32_e32 v49, v177, v51
	ds_bpermute_b32 v246, v234, v198
	ds_bpermute_b32 v247, v234, v199
	v_fma_f32 v54, v174, v50, -v49
	v_fma_f32 v55, v175, v51, -v48
	v_pk_fma_f32 v[48:49], v[174:175], v[50:51], v[48:49] op_sel:[0,0,1] op_sel_hi:[1,1,0]
	s_waitcnt lgkmcnt(1)
	v_cndmask_b32_e64 v38, v246, v198, s[36:37]
	v_mov_b32_e32 v55, v49
	v_add_f32_e32 v34, v34, v54
	v_add_f32_e32 v35, v35, v55
	s_waitcnt lgkmcnt(0)
	v_cndmask_b32_e64 v39, v247, v199, s[36:37]
	v_mul_f32_e32 v48, v176, v34
	v_mul_f32_e32 v49, v177, v35
	s_nop 0
	v_fma_f32 v50, v174, v34, -v49
	v_fma_f32 v51, v175, v35, -v48
	v_pk_fma_f32 v[48:49], v[174:175], v[34:35], v[48:49] op_sel:[0,0,1] op_sel_hi:[1,1,0]
	s_nop 0
	v_mov_b32_e32 v51, v49
	v_add_f32_e32 v214, v38, v50
	v_add_f32_e32 v215, v39, v51
	s_nop 0
	v_cndmask_b32_e64 v35, v215, v35, s[36:37]
	v_cndmask_b32_e64 v34, v214, v34, s[36:37]
	v_fma_f32 v36, v156, v34, v52
	v_fma_f32 v37, v157, v35, v53
	v_mul_f32_e32 v38, v158, v34
	v_mul_f32_e32 v39, v159, v35
	v_fma_f32 v32, v136, v34, v32
	v_fma_f32 v33, v137, v35, v33
	v_add_f32_e64 v48, v36, -v39
	v_add_f32_e64 v49, v37, -v38
	v_add_f32_e32 v36, v36, v39
	v_add_f32_e32 v37, v37, v38
	v_mul_f32_e32 v38, v172, v34
	v_mul_f32_e32 v39, v173, v35
	v_cvt_pk_bf16_f32 v241, v48, v37
	v_fma_f32 v36, v170, v34, v208
	v_fma_f32 v37, v171, v35, v209
	v_mul_f32_e32 v224, v176, v214
	v_mul_f32_e32 v225, v177, v215
	v_add_f32_e64 v48, v36, -v39
	v_add_f32_e64 v49, v37, -v38
	v_add_f32_e32 v36, v36, v39
	v_add_f32_e32 v37, v37, v38
	v_fma_f32 v226, v174, v214, -v225
	v_fma_f32 v227, v175, v215, -v224
	v_cvt_pk_bf16_f32 v240, v48, v37
	v_mul_f32_e32 v36, v138, v34
	v_mul_f32_e32 v37, v139, v35
	v_fma_f32 v214, v174, v214, v225
	v_fma_f32 v215, v175, v215, v224
	v_add_f32_e64 v38, v32, -v37
	v_add_f32_e64 v39, v33, -v36
	v_add_f32_e32 v32, v32, v37
	v_add_f32_e32 v33, v33, v36
	v_mov_b32_e32 v227, v215
	v_cvt_pk_bf16_f32 v205, v38, v33
	v_fma_f32 v32, v174, v34, v198
	v_fma_f32 v33, v175, v35, v199
	v_mul_f32_e32 v34, v176, v34
	v_mul_f32_e32 v35, v177, v35
	v_cndmask_b32_e64 v199, v199, v247, s[36:37]
	v_add_f32_e64 v36, v32, -v35
	v_add_f32_e64 v37, v33, -v34
	v_add_f32_e32 v32, v32, v35
	v_add_f32_e32 v33, v33, v34
	v_cndmask_b32_e64 v198, v198, v246, s[36:37]
	v_cvt_pk_bf16_f32 v201, v36, v33
	v_mul_f32_e32 v32, v192, v0
	v_mul_f32_e32 v33, v193, v0
	v_add_f32_e32 v198, v198, v226
	v_add_f32_e32 v199, v199, v227
	v_fma_f32 v34, v130, v16, v32
	v_fma_f32 v35, v131, v17, v33
	v_fma_f32 v32, v130, v16, -v32
	v_fma_f32 v33, v131, v16, -v33
	v_mov_b32_e32 v164, v199
	v_mov_b32_e32 v35, v33
	v_mov_b32_e32 v32, v1
	v_mov_b32_e32 v33, v17
	v_add_f32_e32 v208, v32, v34
	v_add_f32_e32 v209, v33, v35
	v_mov_b32_e32 v162, v198
	v_mul_f32_e32 v32, v182, v208
	v_mul_f32_e32 v33, v183, v209
	s_nop 0
	v_fma_f32 v34, -v184, v208, v33
	v_fma_f32 v35, -v185, v209, v32
	v_pk_fma_f32 v[32:33], v[184:185], v[208:209], v[32:33] op_sel:[0,0,1] op_sel_hi:[1,1,0]
	s_nop 0
	v_mov_b32_e32 v35, v33
	v_mov_b32_e32 v32, v18
	v_mov_b32_e32 v33, v2
	v_add_f32_e32 v210, v32, v34
	v_add_f32_e32 v211, v33, v35
	v_mov_b32_e32 v2, v19
	v_mul_f32_e32 v32, v184, v210
	v_mul_f32_e32 v33, v185, v211
	s_nop 0
	v_fma_f32 v34, v182, v210, -v33
	v_fma_f32 v35, v183, v211, -v32
	v_pk_fma_f32 v[32:33], v[182:183], v[210:211], v[32:33] op_sel:[0,0,1] op_sel_hi:[1,1,0]
	s_nop 0
	v_mov_b32_e32 v35, v33
	v_add_f32_e32 v212, v2, v34
	v_add_f32_e32 v213, v3, v35
	ds_bpermute_b32 v1, v234, v212
	ds_bpermute_b32 v2, v234, v213
	v_mul_f32_e32 v32, v186, v197
	v_mul_f32_e32 v33, v187, v197
	s_waitcnt lgkmcnt(1)
	v_cndmask_b32_e64 v18, v1, v212, s[36:37]
	v_fma_f32 v34, v152, v160, -v32
	v_fma_f32 v35, v153, v161, -v33
	v_fma_f32 v32, v152, v160, v32
	v_fma_f32 v33, v153, v160, v33
	s_waitcnt lgkmcnt(0)
	v_cndmask_b32_e64 v19, v2, v213, s[36:37]
	v_mov_b32_e32 v35, v33
	v_add_f32_e32 v18, v34, v18
	v_add_f32_e32 v19, v35, v19
	v_cndmask_b32_e64 v3, v213, v2, s[36:37]
	v_mul_f32_e32 v32, v188, v18
	v_mul_f32_e32 v33, v189, v19
	v_cndmask_b32_e64 v248, v18, v160, s[36:37]
	v_cndmask_b32_e64 v249, v19, v197, s[36:37]
	v_fma_f32 v34, v180, v18, -v33
	v_fma_f32 v35, v181, v19, -v32
	v_fma_f32 v18, v180, v18, v33
	v_fma_f32 v19, v181, v19, v32
	v_cndmask_b32_e64 v2, v212, v1, s[36:37]
	v_mov_b32_e32 v35, v19
	v_mul_f32_e32 v18, v194, v4
	v_mul_f32_e32 v19, v195, v4
	v_add_f32_e32 v2, v2, v34
	v_add_f32_e32 v3, v3, v35
	v_fma_f32 v32, v178, v20, -v18
	v_fma_f32 v33, v179, v21, -v19
	v_fma_f32 v18, v178, v20, v18
	v_fma_f32 v19, v179, v20, v19
	v_fma_f32 v16, v123, v248, v16
	v_mov_b32_e32 v33, v19
	v_mov_b32_e32 v18, v21
	v_mov_b32_e32 v19, v5
	v_add_f32_e32 v50, v18, v32
	v_add_f32_e32 v51, v19, v33
	v_fma_f32 v0, v123, v249, v0
	v_mul_f32_e32 v18, v184, v50
	v_mul_f32_e32 v19, v185, v51
	v_fma_f32 v16, -v125, v249, v16
	v_fma_f32 v32, v182, v50, -v19
	v_fma_f32 v33, v183, v51, -v18
	v_pk_fma_f32 v[18:19], v[182:183], v[50:51], v[18:19] op_sel:[0,0,1] op_sel_hi:[1,1,0]
	v_fmac_f32_e32 v0, v125, v248
	v_mov_b32_e32 v33, v19
	v_mov_b32_e32 v18, v22
	v_mov_b32_e32 v19, v6
	v_add_f32_e32 v52, v18, v32
	v_add_f32_e32 v53, v19, v33
	v_mov_b32_e32 v6, v23
	v_mul_f32_e32 v18, v184, v52
	v_mul_f32_e32 v19, v185, v53
	v_cvt_pk_bf16_f32 v0, v16, v0
	v_fma_f32 v32, v182, v52, -v19
	v_fma_f32 v33, v183, v53, -v18
	v_pk_fma_f32 v[18:19], v[182:183], v[52:53], v[18:19] op_sel:[0,0,1] op_sel_hi:[1,1,0]
	ds_write2_b32 v235, v245, v0 offset1:32
	v_mov_b32_e32 v33, v19
	v_add_f32_e32 v54, v6, v32
	v_add_f32_e32 v55, v7, v33
	ds_bpermute_b32 v1, v234, v54
	ds_bpermute_b32 v5, v234, v55
	v_mul_f32_e32 v18, v188, v2
	v_mul_f32_e32 v19, v189, v3
	v_fma_f32 v0, v133, v248, v209
	v_fma_f32 v22, v180, v2, -v19
	v_fma_f32 v23, v181, v3, -v18
	v_pk_fma_f32 v[18:19], v[180:181], v[2:3], v[18:19] op_sel:[0,0,1] op_sel_hi:[1,1,0]
	s_waitcnt lgkmcnt(0)
	v_cndmask_b32_e64 v7, v5, v55, s[36:37]
	v_cndmask_b32_e64 v6, v1, v54, s[36:37]
	v_mov_b32_e32 v23, v19
	v_add_f32_e32 v6, v6, v22
	v_add_f32_e32 v7, v7, v23
	v_cndmask_b32_e64 v1, v54, v1, s[36:37]
	v_cndmask_b32_e64 v17, v6, v2, s[36:37]
	v_cndmask_b32_e64 v21, v7, v3, s[36:37]
	v_mul_f32_e32 v2, v152, v6
	v_mul_f32_e32 v3, v153, v7
	v_mov_b32_e32 v22, v57
	v_sub_f32_e32 v2, v2, v3
	v_add_f32_e32 v163, v1, v2
	v_mul_f32_e32 v2, v186, v6
	v_mul_f32_e32 v3, v187, v7
	v_mov_b32_e32 v6, v40
	v_mov_b32_e32 v7, v8
	v_add_f32_e32 v1, v2, v3
	v_mov_b32_e32 v2, v56
	v_mov_b32_e32 v3, v24
	v_mul_f32_e32 v18, v124, v6
	v_mul_f32_e32 v19, v125, v7
	v_mul_f32_e32 v6, v122, v6
	v_mul_f32_e32 v7, v123, v7
	v_fma_f32 v18, v122, v2, -v18
	v_fma_f32 v19, v123, v3, -v19
	v_fma_f32 v2, v124, v2, v6
	v_fma_f32 v3, v125, v3, v7
	v_mov_b32_e32 v6, v41
	v_mov_b32_e32 v7, v9
	v_mov_b32_e32 v23, v25
	v_add_f32_e32 v34, v6, v2
	v_add_f32_e32 v35, v7, v3
	v_add_f32_e32 v32, v22, v18
	v_add_f32_e32 v33, v23, v19
	v_mul_f32_e32 v2, v124, v34
	v_mul_f32_e32 v3, v125, v35
	v_mov_b32_e32 v6, v58
	v_fma_f32 v2, v122, v32, -v2
	v_fma_f32 v3, v123, v33, -v3
	v_mov_b32_e32 v7, v26
	v_add_f32_e32 v36, v6, v2
	v_add_f32_e32 v37, v7, v3
	v_mul_f32_e32 v2, v124, v32
	v_mul_f32_e32 v3, v125, v33
	v_mov_b32_e32 v6, v42
	v_fma_f32 v2, v122, v34, v2
	v_fma_f32 v3, v123, v35, v3
	v_mov_b32_e32 v7, v10
	v_add_f32_e32 v38, v6, v2
	v_add_f32_e32 v39, v7, v3
	v_mov_b32_e32 v26, v59
	v_mul_f32_e32 v2, v124, v38
	v_mul_f32_e32 v3, v125, v39
	v_mov_b32_e32 v10, v43
	v_fma_f32 v2, v122, v36, -v2
	v_fma_f32 v3, v123, v37, -v3
	v_mov_b32_e32 v6, v44
	v_add_f32_e32 v48, v26, v2
	v_add_f32_e32 v49, v27, v3
	v_mul_f32_e32 v2, v124, v36
	v_mul_f32_e32 v3, v125, v37
	v_mov_b32_e32 v7, v12
	v_fma_f32 v2, v122, v38, v2
	v_fma_f32 v3, v123, v39, v3
	v_cndmask_b32_e64 v5, v55, v5, s[36:37]
	v_add_f32_e32 v42, v10, v2
	v_add_f32_e32 v43, v11, v3
	v_mov_b32_e32 v2, v60
	v_mov_b32_e32 v3, v28
	v_mul_f32_e32 v10, v124, v6
	v_mul_f32_e32 v11, v125, v7
	v_mul_f32_e32 v6, v122, v6
	v_mul_f32_e32 v7, v123, v7
	v_fma_f32 v10, v122, v2, -v10
	v_fma_f32 v11, v123, v3, -v11
	v_mov_b32_e32 v18, v61
	v_mov_b32_e32 v19, v29
	v_fma_f32 v2, v124, v2, v6
	v_fma_f32 v3, v125, v3, v7
	v_mov_b32_e32 v6, v45
	v_mov_b32_e32 v7, v13
	v_add_f32_e32 v165, v5, v1
	ds_bpermute_b32 v1, v234, v48
	ds_bpermute_b32 v9, v234, v49
	v_add_f32_e32 v10, v18, v10
	v_add_f32_e32 v11, v19, v11
	v_add_f32_e32 v18, v6, v2
	v_add_f32_e32 v19, v7, v3
	ds_bpermute_b32 v5, v234, v42
	ds_bpermute_b32 v25, v234, v43
	v_mul_f32_e32 v2, v124, v18
	v_mul_f32_e32 v3, v125, v19
	v_mov_b32_e32 v6, v62
	v_fma_f32 v2, v122, v10, -v2
	v_fma_f32 v3, v123, v11, -v3
	v_mov_b32_e32 v7, v30
	v_add_f32_e32 v22, v6, v2
	v_add_f32_e32 v23, v7, v3
	v_mul_f32_e32 v2, v124, v10
	v_mul_f32_e32 v3, v125, v11
	v_mov_b32_e32 v6, v46
	v_fma_f32 v2, v122, v18, v2
	v_fma_f32 v3, v123, v19, v3
	v_mov_b32_e32 v7, v14
	v_mul_f32_e32 v214, v142, v164
	v_mul_f32_e32 v215, v143, v165
	s_waitcnt lgkmcnt(2)
	v_cndmask_b32_e64 v59, v9, v49, s[36:37]
	v_cndmask_b32_e64 v58, v1, v48, s[36:37]
	v_add_f32_e32 v26, v6, v2
	v_add_f32_e32 v27, v7, v3
	v_mul_f32_e32 v224, v142, v162
	v_mul_f32_e32 v225, v143, v163
	v_fma_f32 v214, v140, v162, -v214
	v_fma_f32 v215, v141, v163, -v215
	s_waitcnt lgkmcnt(0)
	v_cndmask_b32_e64 v197, v25, v43, s[36:37]
	v_cndmask_b32_e64 v196, v5, v42, s[36:37]
	v_mul_f32_e32 v2, v124, v26
	v_mul_f32_e32 v3, v125, v27
	v_add_f32_e32 v58, v58, v214
	v_add_f32_e32 v59, v59, v215
	v_fma_f32 v214, v140, v164, v224
	v_fma_f32 v215, v141, v165, v225
	v_fmac_f32_e32 v208, v133, v249
	v_fma_f32 v2, v122, v22, -v2
	v_fma_f32 v3, v123, v23, -v3
	v_mov_b32_e32 v30, v63
	v_mul_f32_e32 v6, v124, v22
	v_mul_f32_e32 v7, v125, v23
	v_add_f32_e32 v196, v196, v214
	v_add_f32_e32 v197, v197, v215
	v_fma_f32 v0, -v135, v249, v0
	v_fmac_f32_e32 v208, v135, v248
	v_add_f32_e32 v2, v30, v2
	v_add_f32_e32 v3, v31, v3
	v_fma_f32 v6, v122, v26, v6
	v_fma_f32 v7, v123, v27, v7
	v_mov_b32_e32 v14, v47
	v_cndmask_b32_e64 v215, v196, v199, s[36:37]
	v_cndmask_b32_e64 v214, v58, v198, s[36:37]
	v_mul_f32_e32 v198, v142, v196
	v_mul_f32_e32 v199, v143, v197
	v_cvt_pk_bf16_f32 v0, v0, v208
	ds_bpermute_b32 v13, v234, v2
	v_add_f32_e32 v6, v14, v6
	v_add_f32_e32 v7, v15, v7
	ds_bpermute_b32 v45, v234, v3
	v_cndmask_b32_e64 v15, v49, v9, s[36:37]
	v_cndmask_b32_e64 v14, v48, v1, s[36:37]
	v_fma_f32 v198, v140, v58, -v198
	v_fma_f32 v199, v141, v59, -v199
	ds_write2_b32 v235, v244, v0 offset0:68 offset1:100
	v_fma_f32 v0, v237, v248, v210
	v_fmac_f32_e32 v211, v237, v249
	v_add_f32_e32 v198, v14, v198
	v_add_f32_e32 v199, v15, v199
	v_mul_f32_e32 v14, v140, v196
	v_mul_f32_e32 v15, v141, v197
	v_fma_f32 v0, -v238, v249, v0
	v_fmac_f32_e32 v211, v238, v248
	ds_bpermute_b32 v29, v234, v6
	v_cndmask_b32_e64 v31, v43, v25, s[36:37]
	v_cndmask_b32_e64 v30, v42, v5, s[36:37]
	ds_bpermute_b32 v1, v234, v7
	v_fma_f32 v14, v142, v58, v14
	v_fma_f32 v15, v143, v59, v15
	v_cvt_pk_bf16_f32 v0, v0, v211
	v_add_f32_e32 v30, v30, v14
	v_add_f32_e32 v31, v31, v15
	ds_write2_b32 v235, v243, v0 offset0:136 offset1:168
	v_fma_f32 v0, v141, v248, v212
	v_fmac_f32_e32 v213, v141, v249
	v_mul_f32_e32 v14, v142, v30
	v_mul_f32_e32 v15, v143, v31
	v_fma_f32 v0, -v143, v249, v0
	v_fmac_f32_e32 v213, v143, v248
	s_waitcnt lgkmcnt(4)
	v_cndmask_b32_e64 v47, v45, v3, s[36:37]
	v_cndmask_b32_e64 v46, v13, v2, s[36:37]
	v_fma_f32 v14, v140, v198, -v14
	v_fma_f32 v15, v141, v199, -v15
	v_cvt_pk_bf16_f32 v0, v0, v213
	v_add_f32_e32 v46, v46, v14
	v_add_f32_e32 v47, v47, v15
	v_mul_f32_e32 v14, v142, v198
	v_mul_f32_e32 v15, v143, v199
	ds_write2_b32 v235, v242, v0 offset0:204 offset1:236
	v_fma_f32 v0, v123, v17, v20
	v_fma_f32 v4, v123, v21, v4
	s_waitcnt lgkmcnt(2)
	v_cndmask_b32_e64 v63, v1, v7, s[36:37]
	v_cndmask_b32_e64 v62, v29, v6, s[36:37]
	v_fma_f32 v14, v140, v30, v14
	v_fma_f32 v15, v141, v31, v15
	v_fma_f32 v0, -v125, v21, v0
	v_fmac_f32_e32 v4, v125, v17
	v_add_f32_e32 v62, v62, v14
	v_add_f32_e32 v63, v63, v15
	v_cvt_pk_bf16_f32 v0, v0, v4
	v_add_u32_e32 v4, 0x800, v235
	v_mov_b32_e32 v14, v46
	v_mov_b32_e32 v15, v62
	ds_write2_b32 v4, v241, v0 offset0:32 offset1:64
	v_fma_f32 v0, v133, v17, v50
	v_fmac_f32_e32 v51, v133, v21
	v_cndmask_b32_e64 v223, v7, v1, s[36:37]
	v_cndmask_b32_e64 v1, v46, v198, s[36:37]
	v_cndmask_b32_e64 v30, v62, v30, s[36:37]
	v_mul_f32_e32 v14, v150, v14
	v_mul_f32_e32 v15, v151, v15
	v_fma_f32 v0, -v135, v21, v0
	v_fmac_f32_e32 v51, v135, v17
	v_cndmask_b32_e64 v41, v2, v13, s[36:37]
	v_sub_f32_e32 v5, v14, v15
	v_fmac_f32_e32 v60, v122, v1
	v_fmac_f32_e32 v44, v122, v30
	v_cvt_pk_bf16_f32 v0, v0, v51
	v_add_f32_e32 v198, v41, v5
	v_fma_f32 v5, -v124, v30, v60
	v_fmac_f32_e32 v44, v124, v1
	ds_write2_b32 v4, v240, v0 offset0:100 offset1:132
	v_fma_f32 v0, v237, v17, v52
	v_fmac_f32_e32 v53, v237, v21
	v_cvt_pk_bf16_f32 v13, v5, v44
	v_fma_f32 v5, v132, v1, v10
	v_fma_f32 v9, v132, v30, v18
	v_fma_f32 v0, -v238, v21, v0
	v_fmac_f32_e32 v53, v238, v17
	v_fma_f32 v5, -v134, v30, v5
	v_fmac_f32_e32 v9, v134, v1
	v_cvt_pk_bf16_f32 v0, v0, v53
	v_mul_f32_e32 v14, v140, v62
	v_mul_f32_e32 v15, v141, v63
	v_mov_b32_e32 v57, v40
	v_cvt_pk_bf16_f32 v9, v5, v9
	v_fma_f32 v5, v136, v1, v22
	v_fma_f32 v10, v136, v30, v26
	ds_write2_b32 v4, v205, v0 offset0:168 offset1:200
	v_fma_f32 v0, v141, v17, v54
	v_fmac_f32_e32 v55, v141, v21
	v_fma_f32 v224, v142, v46, v14
	v_fma_f32 v225, v143, v47, v15
	v_fma_f32 v14, v156, v214, v56
	v_fma_f32 v15, v157, v215, v57
	v_mul_f32_e32 v40, v158, v214
	v_mul_f32_e32 v41, v159, v215
	v_fma_f32 v5, -v138, v30, v5
	v_fmac_f32_e32 v10, v138, v1
	v_fma_f32 v0, -v143, v21, v0
	v_fmac_f32_e32 v55, v143, v17
	v_add_f32_e64 v56, v14, -v41
	v_add_f32_e64 v57, v15, -v40
	v_add_f32_e32 v14, v14, v41
	v_add_f32_e32 v15, v15, v40
	v_mov_b32_e32 v40, v32
	v_mov_b32_e32 v41, v34
	v_cvt_pk_bf16_f32 v5, v5, v10
	v_cndmask_b32_e64 v10, v59, v163, s[36:37]
	v_cndmask_b32_e64 v18, v197, v165, s[36:37]
	v_cvt_pk_bf16_f32 v0, v0, v55
	v_add_u32_e32 v4, 0xa00, v235
	v_cvt_pk_bf16_f32 v15, v56, v15
	v_fma_f32 v40, v170, v214, v40
	v_fma_f32 v41, v171, v215, v41
	v_mul_f32_e32 v56, v172, v214
	v_mul_f32_e32 v57, v173, v215
	ds_write2_b32 v4, v201, v0 offset0:108 offset1:140
	v_fma_f32 v0, v123, v10, v24
	v_fma_f32 v4, v123, v18, v8
	v_add_f32_e64 v226, v40, -v57
	v_add_f32_e64 v227, v41, -v56
	v_add_f32_e32 v40, v40, v57
	v_add_f32_e32 v41, v41, v56
	v_fma_f32 v0, -v125, v18, v0
	v_fmac_f32_e32 v4, v125, v10
	v_cvt_pk_bf16_f32 v25, v226, v41
	v_mov_b32_e32 v40, v36
	v_mov_b32_e32 v41, v38
	v_cvt_pk_bf16_f32 v0, v0, v4
	v_add_u32_e32 v4, 0x1000, v235
	v_fmac_f32_e32 v33, v133, v10
	v_fmac_f32_e32 v35, v133, v18
	v_fma_f32 v40, v136, v214, v40
	v_fma_f32 v41, v137, v215, v41
	v_mul_f32_e32 v56, v138, v214
	v_mul_f32_e32 v57, v139, v215
	ds_write2_b32 v4, v15, v0 offset0:64 offset1:96
	v_fma_f32 v0, -v135, v18, v33
	v_fmac_f32_e32 v35, v135, v10
	v_add_f32_e64 v226, v40, -v57
	v_add_f32_e64 v227, v41, -v56
	v_add_f32_e32 v40, v40, v57
	v_add_f32_e32 v41, v41, v56
	v_cvt_pk_bf16_f32 v0, v0, v35
	v_fmac_f32_e32 v37, v237, v10
	v_fmac_f32_e32 v39, v237, v18
	v_cndmask_b32_e64 v222, v6, v29, s[36:37]
	v_cvt_pk_bf16_f32 v29, v226, v41
	v_mov_b32_e32 v40, v48
	v_mov_b32_e32 v41, v42
	v_fma_f32 v2, v140, v1, v2
	v_fma_f32 v6, v140, v30, v6
	ds_write2_b32 v4, v25, v0 offset0:132 offset1:164
	v_fma_f32 v0, -v238, v18, v37
	v_fmac_f32_e32 v39, v238, v10
	v_fma_f32 v40, v174, v214, v40
	v_fma_f32 v41, v175, v215, v41
	v_mul_f32_e32 v56, v176, v214
	v_mul_f32_e32 v57, v177, v215
	v_fma_f32 v2, -v142, v30, v2
	v_fmac_f32_e32 v6, v142, v1
	v_cvt_pk_bf16_f32 v0, v0, v39
	v_fmac_f32_e32 v49, v141, v10
	v_fmac_f32_e32 v43, v141, v18
	v_add_f32_e64 v214, v40, -v57
	v_add_f32_e64 v215, v41, -v56
	v_add_f32_e32 v40, v40, v57
	v_add_f32_e32 v41, v41, v56
	v_cvt_pk_bf16_f32 v1, v2, v6
	v_cndmask_b32_e64 v2, v47, v199, s[36:37]
	v_cndmask_b32_e64 v6, v63, v31, s[36:37]
	ds_write2_b32 v4, v29, v0 offset0:200 offset1:232
	v_fma_f32 v0, -v143, v18, v49
	v_fmac_f32_e32 v43, v143, v10
	v_cvt_pk_bf16_f32 v14, v214, v41
	v_cvt_pk_bf16_f32 v0, v0, v43
	v_add_u32_e32 v4, 0x1400, v235
	v_fmac_f32_e32 v28, v123, v2
	v_fmac_f32_e32 v12, v123, v6
	ds_write2_b32 v4, v14, v0 offset0:12 offset1:44
	v_fma_f32 v0, -v125, v6, v28
	v_fmac_f32_e32 v12, v125, v2
	v_cvt_pk_bf16_f32 v0, v0, v12
	v_add_u32_e32 v4, 0x1800, v235
	v_fmac_f32_e32 v11, v133, v2
	v_fmac_f32_e32 v19, v133, v6
	ds_write2_b32 v4, v13, v0 offset0:96 offset1:128
	v_fma_f32 v0, -v135, v6, v11
	v_fmac_f32_e32 v19, v135, v2
	v_cvt_pk_bf16_f32 v0, v0, v19
	v_fmac_f32_e32 v23, v237, v2
	v_fmac_f32_e32 v27, v237, v6
	ds_write2_b32 v4, v9, v0 offset0:164 offset1:196
	v_fma_f32 v0, -v238, v6, v23
	v_fmac_f32_e32 v27, v238, v2
	v_cndmask_b32_e64 v22, v3, v45, s[36:37]
	v_cvt_pk_bf16_f32 v0, v0, v27
	v_add_u32_e32 v4, 0x1a00, v235
	v_fmac_f32_e32 v3, v141, v2
	v_fmac_f32_e32 v7, v141, v6
	ds_write2_b32 v4, v5, v0 offset0:104 offset1:136
	v_fma_f32 v0, -v143, v6, v3
	v_fmac_f32_e32 v7, v143, v2
	v_cvt_pk_bf16_f32 v0, v0, v7
	v_add_u32_e32 v2, 0x1c00, v235
	ds_write2_b32 v2, v1, v0 offset0:44 offset1:76
	s_waitcnt lgkmcnt(0)
	ds_read_b128 v[0:3], v236
	ds_read_b128 v[4:7], v236 offset:64
	s_waitcnt lgkmcnt(1)
	v_mfma_f32_16x16x32_bf16 v[0:3], v[80:83], v[0:3], 0
	v_mov_b32_e32 v62, v47
	v_mul_f32_e32 v30, v152, v62
	v_mul_f32_e32 v31, v153, v63
	v_add_f32_e32 v196, v222, v224
	v_add_f32_e32 v197, v223, v225
	s_waitcnt lgkmcnt(0)
	v_mfma_f32_16x16x32_bf16 v[0:3], v[84:87], v[4:7], v[0:3]
	ds_read_b128 v[4:7], v236 offset:128
	v_sub_f32_e32 v26, v30, v31
	v_add_f32_e32 v160, v22, v26
	s_waitcnt lgkmcnt(0)
	v_mfma_f32_16x16x32_bf16 v[0:3], v[88:91], v[4:7], v[0:3]
	ds_read_b128 v[4:7], v236 offset:192
	s_waitcnt lgkmcnt(0)
	v_mfma_f32_16x16x32_bf16 v[0:3], v[92:95], v[4:7], v[0:3]
	s_waitcnt vmcnt(1)
	v_lshlrev_b32_e32 v4, 16, v206
	v_and_b32_e32 v5, 0xffff0000, v206
	s_nop 4
	v_fma_f32 v0, v96, v4, v0
	v_fma_f32 v1, v97, v5, v1
	s_nop 0
	v_mul_f32_e32 v4, 0x3d372713, v0
	v_mul_f32_e32 v5, 0x3d372713, v1
	v_mul_f32_e32 v4, v0, v4
	v_mul_f32_e32 v5, v1, v5
	v_fma_f32 v4, v0, v4, v0
	v_fma_f32 v5, v1, v5, v1
	v_mul_f32_e32 v4, 0xbfcc422a, v4
	v_mul_f32_e32 v5, 0xbfcc422a, v5
	v_mul_f32_e32 v4, 0x3fb8aa3b, v4
	v_mul_f32_e32 v5, 0x3fb8aa3b, v5
	v_exp_f32_e32 v4, v4
	v_exp_f32_e32 v5, v5
	v_add_f32_e32 v4, 1.0, v4
	v_add_f32_e32 v5, 1.0, v5
	v_rcp_f32_e32 v4, v4
	v_rcp_f32_e32 v5, v5
	s_nop 0
	v_mul_f32_e32 v0, v0, v4
	v_mul_f32_e32 v1, v1, v5
	v_lshlrev_b32_e32 v4, 16, v207
	v_and_b32_e32 v5, 0xffff0000, v207
	v_fma_f32 v2, v98, v4, v2
	v_fma_f32 v3, v99, v5, v3
	v_cvt_pk_bf16_f32 v0, v0, v1
	v_mul_f32_e32 v4, 0x3d372713, v2
	v_mul_f32_e32 v5, 0x3d372713, v3
	v_mul_f32_e32 v4, v2, v4
	v_mul_f32_e32 v5, v3, v5
	v_fma_f32 v4, v2, v4, v2
	v_fma_f32 v5, v3, v5, v3
	v_mul_f32_e32 v4, 0xbfcc422a, v4
	v_mul_f32_e32 v5, 0xbfcc422a, v5
	v_mul_f32_e32 v4, 0x3fb8aa3b, v4
	v_mul_f32_e32 v5, 0x3fb8aa3b, v5
	v_exp_f32_e32 v4, v4
	v_exp_f32_e32 v5, v5
	v_add_f32_e32 v4, 1.0, v4
	v_add_f32_e32 v5, 1.0, v5
	v_rcp_f32_e32 v4, v4
	v_rcp_f32_e32 v5, v5
	s_nop 0
	v_mul_f32_e32 v2, v2, v4
	v_mul_f32_e32 v3, v3, v5
	s_nop 0
	v_cvt_pk_bf16_f32 v1, v2, v3
	v_mad_i64_i32 v[2:3], s[6:7], v204, s35, v[148:149]
	global_store_dwordx2 v[2:3], v[0:1], off
	ds_read_b128 v[0:3], v236 offset:4352
	ds_read_b128 v[4:7], v236 offset:4416
	s_waitcnt lgkmcnt(1)
	v_mfma_f32_16x16x32_bf16 v[0:3], v[80:83], v[0:3], 0
	s_waitcnt lgkmcnt(0)
	v_mfma_f32_16x16x32_bf16 v[0:3], v[84:87], v[4:7], v[0:3]
	ds_read_b128 v[4:7], v236 offset:4480
	s_waitcnt lgkmcnt(0)
	v_mfma_f32_16x16x32_bf16 v[0:3], v[88:91], v[4:7], v[0:3]
	ds_read_b128 v[4:7], v236 offset:4544
	s_waitcnt lgkmcnt(0)
	v_mfma_f32_16x16x32_bf16 v[0:3], v[92:95], v[4:7], v[0:3]
	s_waitcnt vmcnt(1)
	v_lshlrev_b32_e32 v4, 16, v202
	v_and_b32_e32 v5, 0xffff0000, v202
	s_nop 4
	v_fma_f32 v0, v96, v4, v0
	v_fma_f32 v1, v97, v5, v1
	s_nop 0
	v_mul_f32_e32 v4, 0x3d372713, v0
	v_mul_f32_e32 v5, 0x3d372713, v1
	v_mul_f32_e32 v4, v0, v4
	v_mul_f32_e32 v5, v1, v5
	v_fma_f32 v4, v0, v4, v0
	v_fma_f32 v5, v1, v5, v1
	v_mul_f32_e32 v4, 0xbfcc422a, v4
	v_mul_f32_e32 v5, 0xbfcc422a, v5
	v_mul_f32_e32 v4, 0x3fb8aa3b, v4
	v_mul_f32_e32 v5, 0x3fb8aa3b, v5
	v_exp_f32_e32 v4, v4
	v_exp_f32_e32 v5, v5
	v_add_f32_e32 v4, 1.0, v4
	v_add_f32_e32 v5, 1.0, v5
	v_rcp_f32_e32 v4, v4
	v_rcp_f32_e32 v5, v5
	s_nop 0
	v_mul_f32_e32 v0, v0, v4
	v_mul_f32_e32 v1, v1, v5
	v_lshlrev_b32_e32 v4, 16, v203
	v_and_b32_e32 v5, 0xffff0000, v203
	v_fma_f32 v2, v98, v4, v2
	v_fma_f32 v3, v99, v5, v3
	v_cvt_pk_bf16_f32 v0, v0, v1
	v_mul_f32_e32 v4, 0x3d372713, v2
	v_mul_f32_e32 v5, 0x3d372713, v3
	v_mul_f32_e32 v4, v2, v4
	v_mul_f32_e32 v5, v3, v5
	v_fma_f32 v4, v2, v4, v2
	v_fma_f32 v5, v3, v5, v3
	v_mul_f32_e32 v4, 0xbfcc422a, v4
	v_mul_f32_e32 v5, 0xbfcc422a, v5
	v_mul_f32_e32 v4, 0x3fb8aa3b, v4
	v_mul_f32_e32 v5, 0x3fb8aa3b, v5
	v_exp_f32_e32 v4, v4
	v_exp_f32_e32 v5, v5
	v_add_f32_e32 v4, 1.0, v4
	v_add_f32_e32 v5, 1.0, v5
	v_rcp_f32_e32 v4, v4
	v_rcp_f32_e32 v5, v5
	s_nop 0
	v_mul_f32_e32 v2, v2, v4
	v_mul_f32_e32 v3, v3, v5
	s_nop 0
	v_cvt_pk_bf16_f32 v1, v2, v3
	v_mad_i64_i32 v[2:3], s[6:7], v200, s35, v[148:149]
	global_store_dwordx2 v[2:3], v[0:1], off
	s_waitcnt lgkmcnt(0)
	s_mov_b64 s[6:7], 0
	s_cbranch_vccz .LBB0_185
	s_add_i32 s10, s10, 1
	s_cmp_eq_u32 s10, 4
	s_cbranch_scc0 .LBB0_184
	s_cmp_eq_u32 s33, 0x100
	s_cbranch_scc0 .Ls5_gen1
	s_add_i32 s4, s4, 8
	s_add_i32 s8, s8, 8
	v_readlane_b32 s6, v255, 29
	s_mul_i32 s6, s6, 12
	s_sub_i32 s6, s4, s6
	s_cmp_gt_i32 s6, 11
	s_cbranch_scc0 .LBB0_179
	s_branch .LBB0_188

.LBB0_203:
	v_sub_f32_e32 v103, v103, v234
	v_sub_f32_e32 v102, v102, v234
	v_sub_f32_e32 v101, v101, v234
	v_sub_f32_e32 v100, v100, v234
	v_sub_f32_e32 v99, v99, v234
	v_sub_f32_e32 v98, v98, v234
	v_sub_f32_e32 v97, v97, v234
	v_sub_f32_e32 v96, v96, v234
	v_sub_f32_e32 v119, v119, v234
	v_sub_f32_e32 v118, v118, v234
	v_sub_f32_e32 v117, v117, v234
	v_sub_f32_e32 v116, v116, v234
	v_sub_f32_e32 v115, v115, v234
	v_sub_f32_e32 v114, v114, v234
	v_sub_f32_e32 v113, v113, v234
	v_sub_f32_e32 v112, v112, v234
	v_sub_f32_e32 v107, v107, v234
	v_sub_f32_e32 v106, v106, v234
	v_sub_f32_e32 v105, v105, v234
	v_sub_f32_e32 v104, v104, v234
	v_sub_f32_e32 v123, v123, v234
	v_sub_f32_e32 v122, v122, v234
	v_sub_f32_e32 v121, v121, v234
	v_sub_f32_e32 v120, v120, v234
	v_exp_f32_e32 v96, v96
	v_exp_f32_e32 v97, v97
	v_exp_f32_e32 v98, v98
	v_exp_f32_e32 v99, v99
	v_exp_f32_e32 v100, v100
	v_exp_f32_e32 v101, v101
	v_exp_f32_e32 v102, v102
	v_exp_f32_e32 v103, v103
	v_exp_f32_e32 v112, v112
	v_exp_f32_e32 v113, v113
	v_exp_f32_e32 v114, v114
	v_exp_f32_e32 v115, v115
	v_exp_f32_e32 v116, v116
	v_exp_f32_e32 v117, v117
	v_exp_f32_e32 v118, v118
	v_exp_f32_e32 v119, v119
	v_sub_f32_e32 v111, v111, v234
	v_sub_f32_e32 v110, v110, v234
	v_sub_f32_e32 v109, v109, v234
	v_sub_f32_e32 v108, v108, v234
	v_sub_f32_e32 v127, v127, v234
	v_sub_f32_e32 v126, v126, v234
	v_sub_f32_e32 v125, v125, v234
	v_sub_f32_e32 v124, v124, v234
	v_exp_f32_e32 v104, v104
	v_exp_f32_e32 v105, v105
	v_exp_f32_e32 v106, v106
	v_exp_f32_e32 v107, v107
	v_exp_f32_e32 v120, v120
	v_exp_f32_e32 v122, v122
	v_exp_f32_e32 v123, v123
	v_exp_f32_e32 v121, v121
	v_exp_f32_e32 v108, v108
	v_exp_f32_e32 v109, v109
	v_exp_f32_e32 v110, v110
	v_exp_f32_e32 v111, v111
	v_exp_f32_e32 v124, v124
	v_exp_f32_e32 v125, v125
	v_exp_f32_e32 v126, v126
	v_exp_f32_e32 v127, v127
	v_add_f32_e32 v226, v100, v116
	v_add_f32_e32 v227, v101, v117
	v_add_f32_e32 v236, v96, v112
	v_add_f32_e32 v237, v97, v113
	v_add_f32_e32 v238, v102, v118
	v_add_f32_e32 v239, v103, v119
	v_add_f32_e32 v240, v98, v114
	v_add_f32_e32 v241, v99, v115
	v_add_f32_e32 v222, v106, v122
	v_add_f32_e32 v223, v107, v123
	v_add_f32_e32 v224, v104, v120
	v_add_f32_e32 v225, v105, v121
	v_add_f32_e32 v238, v240, v238
	v_add_f32_e32 v239, v241, v239
	v_add_f32_e32 v226, v236, v226
	v_add_f32_e32 v227, v237, v227
	v_add_f32_e32 v162, v108, v124
	v_add_f32_e32 v163, v109, v125
	v_add_f32_e32 v164, v110, v126
	v_add_f32_e32 v165, v111, v127
	v_add_f32_e32 v224, v224, v226
	v_add_f32_e32 v225, v225, v227
	v_add_f32_e32 v222, v222, v238
	v_add_f32_e32 v223, v223, v239
	v_add_f32_e32 v162, v162, v224
	v_add_f32_e32 v163, v163, v225
	v_add_f32_e32 v164, v164, v222
	v_add_f32_e32 v165, v165, v223
	v_add_f32_e32 v162, v162, v163
	v_add_f32_e32 v163, v164, v165
	v_add_f32_e32 v162, v162, v163
	v_fmac_f32_e32 v162, v215, v170
	s_setprio 1
	ds_read_b128 v[222:225], v209
	ds_read_b128 v[240:243], v209 offset:4608
	ds_read_b128 v[244:247], v209 offset:9216
	ds_read_b128 v[248:251], v209 offset:13824
	v_cvt_pk_bf16_f32 v236, v96, v97
	v_cvt_pk_bf16_f32 v237, v98, v99
	v_cvt_pk_bf16_f32 v238, v100, v101
	v_cvt_pk_bf16_f32 v239, v102, v103
	s_waitcnt lgkmcnt(3)
	s_nop 0
	v_mfma_f32_32x32x16_bf16 v[48:63], v[222:225], v[236:239], v[48:63]
	ds_read_b128 v[222:225], v209 offset:32
	s_waitcnt lgkmcnt(3)
	v_mfma_f32_32x32x16_bf16 v[32:47], v[240:243], v[236:239], v[32:47]
	ds_read_b128 v[240:243], v209 offset:4640
	s_waitcnt lgkmcnt(3)
	v_mfma_f32_32x32x16_bf16 v[16:31], v[244:247], v[236:239], v[16:31]
	ds_read_b128 v[244:247], v209 offset:9248
	s_waitcnt lgkmcnt(3)
	v_mfma_f32_32x32x16_bf16 v[0:15], v[248:251], v[236:239], v[0:15]
	ds_read_b128 v[248:251], v209 offset:13856
	v_cvt_pk_bf16_f32 v236, v104, v105
	v_cvt_pk_bf16_f32 v237, v106, v107
	v_cvt_pk_bf16_f32 v238, v108, v109
	v_cvt_pk_bf16_f32 v239, v110, v111
	s_waitcnt lgkmcnt(3)
	s_nop 0
	v_mfma_f32_32x32x16_bf16 v[48:63], v[222:225], v[236:239], v[48:63]
	ds_read_b128 v[222:225], v209 offset:64
	s_waitcnt lgkmcnt(3)
	v_mfma_f32_32x32x16_bf16 v[32:47], v[240:243], v[236:239], v[32:47]
	ds_read_b128 v[240:243], v209 offset:4672
	s_waitcnt lgkmcnt(3)
	v_mfma_f32_32x32x16_bf16 v[16:31], v[244:247], v[236:239], v[16:31]
	ds_read_b128 v[244:247], v209 offset:9280
	s_waitcnt lgkmcnt(3)
	v_mfma_f32_32x32x16_bf16 v[0:15], v[248:251], v[236:239], v[0:15]
	ds_read_b128 v[248:251], v209 offset:13888
	v_cvt_pk_bf16_f32 v236, v112, v113
	v_cvt_pk_bf16_f32 v237, v114, v115
	v_cvt_pk_bf16_f32 v238, v116, v117
	v_cvt_pk_bf16_f32 v239, v118, v119
	s_waitcnt lgkmcnt(3)
	s_nop 0
	v_mfma_f32_32x32x16_bf16 v[48:63], v[222:225], v[236:239], v[48:63]
	ds_read_b128 v[222:225], v209 offset:96
	s_waitcnt lgkmcnt(3)
	v_mfma_f32_32x32x16_bf16 v[32:47], v[240:243], v[236:239], v[32:47]
	ds_read_b128 v[240:243], v209 offset:4704
	s_waitcnt lgkmcnt(3)
	v_mfma_f32_32x32x16_bf16 v[16:31], v[244:247], v[236:239], v[16:31]
	ds_read_b128 v[244:247], v209 offset:9312
	s_waitcnt lgkmcnt(3)
	v_mfma_f32_32x32x16_bf16 v[0:15], v[248:251], v[236:239], v[0:15]
	ds_read_b128 v[248:251], v209 offset:13920
	v_cvt_pk_bf16_f32 v236, v120, v121
	v_cvt_pk_bf16_f32 v237, v122, v123
	v_cvt_pk_bf16_f32 v238, v124, v125
	v_cvt_pk_bf16_f32 v239, v126, v127
	s_waitcnt lgkmcnt(3)
	s_nop 0
	v_mfma_f32_32x32x16_bf16 v[48:63], v[222:225], v[236:239], v[48:63]
	s_waitcnt lgkmcnt(2)
	v_mfma_f32_32x32x16_bf16 v[32:47], v[240:243], v[236:239], v[32:47]
	s_waitcnt lgkmcnt(1)
	v_mfma_f32_32x32x16_bf16 v[16:31], v[244:247], v[236:239], v[16:31]
	s_waitcnt lgkmcnt(0)
	v_mfma_f32_32x32x16_bf16 v[0:15], v[248:251], v[236:239], v[0:15]
	s_setprio 0
	v_mov_b32_e32 v170, v234
	v_mov_b32_e32 v215, v162

.Lda_upd0:
	v_max_f32_e32 v234, v170, v162
	v_sub_f32_e32 v162, v170, v234
	v_exp_f32_e32 v170, v162
	s_nop 0
	v_mul_f32_e32 v62, v62, v170
	v_mul_f32_e32 v63, v63, v170
	v_mul_f32_e32 v60, v60, v170
	v_mul_f32_e32 v61, v61, v170
	v_mul_f32_e32 v58, v58, v170
	v_mul_f32_e32 v59, v59, v170
	v_mul_f32_e32 v56, v56, v170
	v_mul_f32_e32 v57, v57, v170
	v_mul_f32_e32 v54, v54, v170
	v_mul_f32_e32 v55, v55, v170
	v_mul_f32_e32 v52, v52, v170
	v_mul_f32_e32 v53, v53, v170
	v_mul_f32_e32 v50, v50, v170
	v_mul_f32_e32 v51, v51, v170
	v_mul_f32_e32 v48, v48, v170
	v_mul_f32_e32 v49, v49, v170
	v_mul_f32_e32 v46, v46, v170
	v_mul_f32_e32 v47, v47, v170
	v_mul_f32_e32 v44, v44, v170
	v_mul_f32_e32 v45, v45, v170
	v_mul_f32_e32 v42, v42, v170
	v_mul_f32_e32 v43, v43, v170
	v_mul_f32_e32 v40, v40, v170
	v_mul_f32_e32 v41, v41, v170
	v_mul_f32_e32 v38, v38, v170
	v_mul_f32_e32 v39, v39, v170
	v_mul_f32_e32 v36, v36, v170
	v_mul_f32_e32 v37, v37, v170
	v_mul_f32_e32 v34, v34, v170
	v_mul_f32_e32 v35, v35, v170
	v_mul_f32_e32 v32, v32, v170
	v_mul_f32_e32 v33, v33, v170
	v_mul_f32_e32 v30, v30, v170
	v_mul_f32_e32 v31, v31, v170
	v_mul_f32_e32 v28, v28, v170
	v_mul_f32_e32 v29, v29, v170
	v_mul_f32_e32 v26, v26, v170
	v_mul_f32_e32 v27, v27, v170
	v_mul_f32_e32 v24, v24, v170
	v_mul_f32_e32 v25, v25, v170
	v_mul_f32_e32 v22, v22, v170
	v_mul_f32_e32 v23, v23, v170
	v_mul_f32_e32 v20, v20, v170
	v_mul_f32_e32 v21, v21, v170
	v_mul_f32_e32 v18, v18, v170
	v_mul_f32_e32 v19, v19, v170
	v_mul_f32_e32 v16, v16, v170
	v_mul_f32_e32 v17, v17, v170
	v_mul_f32_e32 v14, v14, v170
	v_mul_f32_e32 v15, v15, v170
	v_mul_f32_e32 v12, v12, v170
	v_mul_f32_e32 v13, v13, v170
	v_mul_f32_e32 v10, v10, v170
	v_mul_f32_e32 v11, v11, v170
	v_mul_f32_e32 v8, v8, v170
	v_mul_f32_e32 v9, v9, v170
	v_mul_f32_e32 v6, v6, v170
	v_mul_f32_e32 v7, v7, v170
	v_mul_f32_e32 v4, v4, v170
	v_mul_f32_e32 v5, v5, v170
	v_mul_f32_e32 v2, v2, v170
	v_mul_f32_e32 v3, v3, v170
	v_mul_f32_e32 v0, v0, v170
	v_mul_f32_e32 v1, v1, v170
.LBB0_212:
	v_sub_f32_e32 v71, v71, v234
	v_sub_f32_e32 v70, v70, v234
	v_sub_f32_e32 v69, v69, v234
	v_sub_f32_e32 v68, v68, v234
	v_sub_f32_e32 v67, v67, v234
	v_sub_f32_e32 v66, v66, v234
	v_sub_f32_e32 v65, v65, v234
	v_sub_f32_e32 v64, v64, v234
	v_sub_f32_e32 v87, v87, v234
	v_sub_f32_e32 v86, v86, v234
	v_sub_f32_e32 v85, v85, v234
	v_sub_f32_e32 v84, v84, v234
	v_sub_f32_e32 v83, v83, v234
	v_sub_f32_e32 v82, v82, v234
	v_sub_f32_e32 v81, v81, v234
	v_sub_f32_e32 v80, v80, v234
	v_sub_f32_e32 v75, v75, v234
	v_sub_f32_e32 v74, v74, v234
	v_sub_f32_e32 v73, v73, v234
	v_sub_f32_e32 v72, v72, v234
	v_sub_f32_e32 v91, v91, v234
	v_sub_f32_e32 v90, v90, v234
	v_sub_f32_e32 v89, v89, v234
	v_sub_f32_e32 v88, v88, v234
	v_exp_f32_e32 v64, v64
	v_exp_f32_e32 v65, v65
	v_exp_f32_e32 v66, v66
	v_exp_f32_e32 v67, v67
	v_exp_f32_e32 v68, v68
	v_exp_f32_e32 v69, v69
	v_exp_f32_e32 v70, v70
	v_exp_f32_e32 v71, v71
	v_exp_f32_e32 v80, v80
	v_exp_f32_e32 v81, v81
	v_exp_f32_e32 v82, v82
	v_exp_f32_e32 v83, v83
	v_exp_f32_e32 v84, v84
	v_exp_f32_e32 v85, v85
	v_exp_f32_e32 v86, v86
	v_exp_f32_e32 v87, v87
	v_sub_f32_e32 v79, v79, v234
	v_sub_f32_e32 v78, v78, v234
	v_sub_f32_e32 v77, v77, v234
	v_sub_f32_e32 v76, v76, v234
	v_sub_f32_e32 v95, v95, v234
	v_sub_f32_e32 v94, v94, v234
	v_sub_f32_e32 v93, v93, v234
	v_sub_f32_e32 v92, v92, v234
	v_exp_f32_e32 v72, v72
	v_exp_f32_e32 v73, v73
	v_exp_f32_e32 v74, v74
	v_exp_f32_e32 v75, v75
	v_exp_f32_e32 v88, v88
	v_exp_f32_e32 v90, v90
	v_exp_f32_e32 v91, v91
	v_exp_f32_e32 v89, v89
	v_exp_f32_e32 v76, v76
	v_exp_f32_e32 v77, v77
	v_exp_f32_e32 v78, v78
	v_exp_f32_e32 v79, v79
	v_exp_f32_e32 v92, v92
	v_exp_f32_e32 v93, v93
	v_exp_f32_e32 v94, v94
	v_exp_f32_e32 v95, v95
	v_add_f32_e32 v226, v68, v84
	v_add_f32_e32 v227, v69, v85
	v_add_f32_e32 v236, v64, v80
	v_add_f32_e32 v237, v65, v81
	v_add_f32_e32 v238, v70, v86
	v_add_f32_e32 v239, v71, v87
	v_add_f32_e32 v240, v66, v82
	v_add_f32_e32 v241, v67, v83
	v_add_f32_e32 v222, v74, v90
	v_add_f32_e32 v223, v75, v91
	v_add_f32_e32 v224, v72, v88
	v_add_f32_e32 v225, v73, v89
	v_add_f32_e32 v238, v240, v238
	v_add_f32_e32 v239, v241, v239
	v_add_f32_e32 v226, v236, v226
	v_add_f32_e32 v227, v237, v227
	v_add_f32_e32 v162, v76, v92
	v_add_f32_e32 v163, v77, v93
	v_add_f32_e32 v164, v78, v94
	v_add_f32_e32 v165, v79, v95
	v_add_f32_e32 v224, v224, v226
	v_add_f32_e32 v225, v225, v227
	v_add_f32_e32 v222, v222, v238
	v_add_f32_e32 v223, v223, v239
	v_add_f32_e32 v162, v162, v224
	v_add_f32_e32 v163, v163, v225
	v_add_f32_e32 v164, v164, v222
	v_add_f32_e32 v165, v165, v223
	v_add_f32_e32 v162, v162, v163
	v_add_f32_e32 v163, v164, v165
	v_add_f32_e32 v162, v162, v163
	v_fmac_f32_e32 v162, v215, v170
	s_setprio 1
	v_add_u32_e32 v163, v202, v169
	ds_read_b128 v[222:225], v163 offset:52224
	ds_read_b128 v[240:243], v163 offset:56832
	ds_read_b128 v[244:247], v163 offset:61440
	ds_read_b128 v[248:251], v207 offset:52224
	v_cvt_pk_bf16_f32 v236, v64, v65
	v_cvt_pk_bf16_f32 v237, v66, v67
	v_cvt_pk_bf16_f32 v238, v68, v69
	v_cvt_pk_bf16_f32 v239, v70, v71
	s_waitcnt lgkmcnt(3)
	s_nop 0
	v_mfma_f32_32x32x16_bf16 v[48:63], v[222:225], v[236:239], v[48:63]
	ds_read_b128 v[222:225], v163 offset:52256
	s_waitcnt lgkmcnt(3)
	v_mfma_f32_32x32x16_bf16 v[32:47], v[240:243], v[236:239], v[32:47]
	ds_read_b128 v[240:243], v163 offset:56864
	s_waitcnt lgkmcnt(3)
	v_mfma_f32_32x32x16_bf16 v[16:31], v[244:247], v[236:239], v[16:31]
	ds_read_b128 v[244:247], v163 offset:61472
	s_waitcnt lgkmcnt(3)
	v_mfma_f32_32x32x16_bf16 v[0:15], v[248:251], v[236:239], v[0:15]
	ds_read_b128 v[248:251], v207 offset:52256
	v_cvt_pk_bf16_f32 v236, v72, v73
	v_cvt_pk_bf16_f32 v237, v74, v75
	v_cvt_pk_bf16_f32 v238, v76, v77
	v_cvt_pk_bf16_f32 v239, v78, v79
	s_waitcnt lgkmcnt(3)
	s_nop 0
	v_mfma_f32_32x32x16_bf16 v[48:63], v[222:225], v[236:239], v[48:63]
	ds_read_b128 v[222:225], v163 offset:52288
	s_waitcnt lgkmcnt(3)
	v_mfma_f32_32x32x16_bf16 v[32:47], v[240:243], v[236:239], v[32:47]
	ds_read_b128 v[240:243], v163 offset:56896
	s_waitcnt lgkmcnt(3)
	v_mfma_f32_32x32x16_bf16 v[16:31], v[244:247], v[236:239], v[16:31]
	ds_read_b128 v[244:247], v163 offset:61504
	s_waitcnt lgkmcnt(3)
	v_mfma_f32_32x32x16_bf16 v[0:15], v[248:251], v[236:239], v[0:15]
	ds_read_b128 v[248:251], v207 offset:52288
	v_cvt_pk_bf16_f32 v236, v80, v81
	v_cvt_pk_bf16_f32 v237, v82, v83
	v_cvt_pk_bf16_f32 v238, v84, v85
	v_cvt_pk_bf16_f32 v239, v86, v87
	s_waitcnt lgkmcnt(3)
	s_nop 0
	v_mfma_f32_32x32x16_bf16 v[48:63], v[222:225], v[236:239], v[48:63]
	ds_read_b128 v[222:225], v163 offset:52320
	s_waitcnt lgkmcnt(3)
	v_mfma_f32_32x32x16_bf16 v[32:47], v[240:243], v[236:239], v[32:47]
	ds_read_b128 v[240:243], v163 offset:56928
	s_waitcnt lgkmcnt(3)
	v_mfma_f32_32x32x16_bf16 v[16:31], v[244:247], v[236:239], v[16:31]
	ds_read_b128 v[244:247], v163 offset:61536
	s_waitcnt lgkmcnt(3)
	v_mfma_f32_32x32x16_bf16 v[0:15], v[248:251], v[236:239], v[0:15]
	ds_read_b128 v[248:251], v207 offset:52320
	v_cvt_pk_bf16_f32 v236, v88, v89
	v_cvt_pk_bf16_f32 v237, v90, v91
	v_cvt_pk_bf16_f32 v238, v92, v93
	v_cvt_pk_bf16_f32 v239, v94, v95
	s_waitcnt lgkmcnt(3)
	s_nop 0
	v_mfma_f32_32x32x16_bf16 v[48:63], v[222:225], v[236:239], v[48:63]
	s_waitcnt lgkmcnt(2)
	v_mfma_f32_32x32x16_bf16 v[32:47], v[240:243], v[236:239], v[32:47]
	s_waitcnt lgkmcnt(1)
	v_mfma_f32_32x32x16_bf16 v[16:31], v[244:247], v[236:239], v[16:31]
	s_waitcnt lgkmcnt(0)
	v_mfma_f32_32x32x16_bf16 v[0:15], v[248:251], v[236:239], v[0:15]
	s_setprio 0
	v_mov_b32_e32 v170, v234
	v_mov_b32_e32 v215, v162

.Lda_upd1:
	v_max_f32_e32 v234, v170, v162
	v_sub_f32_e32 v162, v170, v234
	v_exp_f32_e32 v170, v162
	s_nop 0
	v_mul_f32_e32 v62, v62, v170
	v_mul_f32_e32 v63, v63, v170
	v_mul_f32_e32 v60, v60, v170
	v_mul_f32_e32 v61, v61, v170
	v_mul_f32_e32 v58, v58, v170
	v_mul_f32_e32 v59, v59, v170
	v_mul_f32_e32 v56, v56, v170
	v_mul_f32_e32 v57, v57, v170
	v_mul_f32_e32 v54, v54, v170
	v_mul_f32_e32 v55, v55, v170
	v_mul_f32_e32 v52, v52, v170
	v_mul_f32_e32 v53, v53, v170
	v_mul_f32_e32 v50, v50, v170
	v_mul_f32_e32 v51, v51, v170
	v_mul_f32_e32 v48, v48, v170
	v_mul_f32_e32 v49, v49, v170
	v_mul_f32_e32 v46, v46, v170
	v_mul_f32_e32 v47, v47, v170
	v_mul_f32_e32 v44, v44, v170
	v_mul_f32_e32 v45, v45, v170
	v_mul_f32_e32 v42, v42, v170
	v_mul_f32_e32 v43, v43, v170
	v_mul_f32_e32 v40, v40, v170
	v_mul_f32_e32 v41, v41, v170
	v_mul_f32_e32 v38, v38, v170
	v_mul_f32_e32 v39, v39, v170
	v_mul_f32_e32 v36, v36, v170
	v_mul_f32_e32 v37, v37, v170
	v_mul_f32_e32 v34, v34, v170
	v_mul_f32_e32 v35, v35, v170
	v_mul_f32_e32 v32, v32, v170
	v_mul_f32_e32 v33, v33, v170
	v_mul_f32_e32 v30, v30, v170
	v_mul_f32_e32 v31, v31, v170
	v_mul_f32_e32 v28, v28, v170
	v_mul_f32_e32 v29, v29, v170
	v_mul_f32_e32 v26, v26, v170
	v_mul_f32_e32 v27, v27, v170
	v_mul_f32_e32 v24, v24, v170
	v_mul_f32_e32 v25, v25, v170
	v_mul_f32_e32 v22, v22, v170
	v_mul_f32_e32 v23, v23, v170
	v_mul_f32_e32 v20, v20, v170
	v_mul_f32_e32 v21, v21, v170
	v_mul_f32_e32 v18, v18, v170
	v_mul_f32_e32 v19, v19, v170
	v_mul_f32_e32 v16, v16, v170
	v_mul_f32_e32 v17, v17, v170
	v_mul_f32_e32 v14, v14, v170
	v_mul_f32_e32 v15, v15, v170
	v_mul_f32_e32 v12, v12, v170
	v_mul_f32_e32 v13, v13, v170
	v_mul_f32_e32 v10, v10, v170
	v_mul_f32_e32 v11, v11, v170
	v_mul_f32_e32 v8, v8, v170
	v_mul_f32_e32 v9, v9, v170
	v_mul_f32_e32 v6, v6, v170
	v_mul_f32_e32 v7, v7, v170
	v_mul_f32_e32 v4, v4, v170
	v_mul_f32_e32 v5, v5, v170
	v_mul_f32_e32 v2, v2, v170
	v_mul_f32_e32 v3, v3, v170
	v_mul_f32_e32 v0, v0, v170
	v_mul_f32_e32 v1, v1, v170
	s_branch .LBB0_203

.LBB0_612:
	s_and_b64 vcc, exec, s[8:9]
	s_cbranch_vccz .LBB0_611
	v_lshlrev_b64 v[154:155], 6, v[150:151]
	v_lshl_add_u64 v[154:155], v[142:143], 0, v[154:155]
	v_add_co_u32_e32 v156, vcc, 0x2000, v154
	s_nop 1
	v_addc_co_u32_e32 v157, vcc, 0, v155, vcc
	global_load_dwordx4 v[170:173], v[154:155], off
	global_load_dwordx4 v[174:177], v[154:155], off offset:1024
	global_load_dwordx4 v[178:181], v[154:155], off offset:2048
	global_load_dwordx4 v[182:185], v[154:155], off offset:3072
	global_load_dwordx4 v[186:189], v[156:157], off
	global_load_dwordx4 v[200:203], v[156:157], off offset:1024
	global_load_dwordx4 v[204:207], v[156:157], off offset:2048
	global_load_dwordx4 v[208:211], v[156:157], off offset:3072
	v_or_b32_e32 v152, s91, v136
	v_lshl_or_b32 v152, s14, 7, v152
	v_ashrrev_i32_e32 v153, 31, v152
	v_mov_b64_e32 v[212:213], s[64:65]
	v_lshlrev_b64 v[214:215], 1, v[152:153]
	s_waitcnt vmcnt(0)
	v_add_f32_e32 v170, v171, v170
	v_add_f32_e32 v172, v172, v173
	v_add_f32_e32 v174, v175, v174
	v_add_f32_e32 v176, v176, v177
	v_add_f32_e32 v178, v179, v178
	v_add_f32_e32 v180, v180, v181
	v_add_f32_e32 v182, v183, v182
	v_add_f32_e32 v184, v184, v185
	v_add_f32_e32 v186, v187, v186
	v_add_f32_e32 v188, v188, v189
	v_add_f32_e32 v200, v201, v200
	v_add_f32_e32 v202, v202, v203
	v_add_f32_e32 v204, v205, v204
	v_add_f32_e32 v206, v206, v207
	v_add_f32_e32 v208, v209, v208
	v_add_f32_e32 v210, v210, v211
	v_add_f32_e32 v170, v170, v172
	v_add_f32_e32 v174, v174, v176
	v_add_f32_e32 v178, v178, v180
	v_add_f32_e32 v182, v182, v184
	v_add_f32_e32 v186, v186, v188
	v_add_f32_e32 v200, v200, v202
	v_add_f32_e32 v204, v204, v206
	v_add_f32_e32 v208, v208, v210
	ds_bpermute_b32 v171, v197, v170
	ds_bpermute_b32 v175, v197, v174
	ds_bpermute_b32 v179, v197, v178
	ds_bpermute_b32 v183, v197, v182
	ds_bpermute_b32 v187, v197, v186
	ds_bpermute_b32 v201, v197, v200
	ds_bpermute_b32 v205, v197, v204
	ds_bpermute_b32 v209, v197, v208
	s_waitcnt lgkmcnt(0)
	v_add_f32_e32 v170, v170, v171
	v_add_f32_e32 v174, v174, v175
	v_add_f32_e32 v178, v178, v179
	v_add_f32_e32 v182, v182, v183
	v_add_f32_e32 v186, v186, v187
	v_add_f32_e32 v200, v200, v201
	v_add_f32_e32 v204, v204, v205
	v_add_f32_e32 v208, v208, v209
	ds_bpermute_b32 v171, v198, v170
	ds_bpermute_b32 v175, v198, v174
	ds_bpermute_b32 v179, v198, v178
	ds_bpermute_b32 v183, v198, v182
	ds_bpermute_b32 v187, v198, v186
	ds_bpermute_b32 v201, v198, v200
	ds_bpermute_b32 v205, v198, v204
	ds_bpermute_b32 v209, v198, v208
	s_waitcnt lgkmcnt(0)
	v_add_f32_e32 v170, v170, v171
	v_add_f32_e32 v174, v174, v175
	v_add_f32_e32 v178, v178, v179
	v_add_f32_e32 v182, v182, v183
	v_add_f32_e32 v186, v186, v187
	v_add_f32_e32 v200, v200, v201
	v_add_f32_e32 v204, v204, v205
	v_add_f32_e32 v208, v208, v209
	v_fmamk_f32 v170, v170, 0x3a800000, v216
	v_fmamk_f32 v174, v174, 0x3a800000, v216
	v_fmamk_f32 v178, v178, 0x3a800000, v216
	v_fmamk_f32 v182, v182, 0x3a800000, v216
	v_fmamk_f32 v186, v186, 0x3a800000, v216
	v_fmamk_f32 v200, v200, 0x3a800000, v216
	v_fmamk_f32 v204, v204, 0x3a800000, v216
	v_fmamk_f32 v208, v208, 0x3a800000, v216
	v_mov_b32_e32 v172, v170
	v_mov_b32_e32 v176, v174
	v_mov_b32_e32 v180, v178
	v_mov_b32_e32 v184, v182
	v_mov_b32_e32 v188, v186
	v_mov_b32_e32 v202, v200
	v_mov_b32_e32 v206, v204
	v_mov_b32_e32 v210, v208
	v_cmp_gt_f32_e32 vcc, s29, v170
	v_mul_f32_e32 v171, 0x4b800000, v170
	s_nop 0
	v_cndmask_b32_e32 v170, v170, v171, vcc
	v_rsq_f32_e32 v170, v170
	s_nop 0
	v_mul_f32_e32 v171, 0x45800000, v170
	v_cndmask_b32_e32 v170, v170, v171, vcc
	v_cmp_gt_f32_e32 vcc, s29, v174
	v_mul_f32_e32 v175, 0x4b800000, v174
	s_nop 0
	v_cndmask_b32_e32 v174, v174, v175, vcc
	v_rsq_f32_e32 v174, v174
	s_nop 0
	v_mul_f32_e32 v175, 0x45800000, v174
	v_cndmask_b32_e32 v174, v174, v175, vcc
	v_cmp_gt_f32_e32 vcc, s29, v178
	v_mul_f32_e32 v179, 0x4b800000, v178
	s_nop 0
	v_cndmask_b32_e32 v178, v178, v179, vcc
	v_rsq_f32_e32 v178, v178
	s_nop 0
	v_mul_f32_e32 v179, 0x45800000, v178
	v_cndmask_b32_e32 v178, v178, v179, vcc
	v_cmp_gt_f32_e32 vcc, s29, v182
	v_mul_f32_e32 v183, 0x4b800000, v182
	s_nop 0
	v_cndmask_b32_e32 v182, v182, v183, vcc
	v_rsq_f32_e32 v182, v182
	s_nop 0
	v_mul_f32_e32 v183, 0x45800000, v182
	v_cndmask_b32_e32 v182, v182, v183, vcc
	v_cmp_gt_f32_e32 vcc, s29, v186
	v_mul_f32_e32 v187, 0x4b800000, v186
	s_nop 0
	v_cndmask_b32_e32 v186, v186, v187, vcc
	v_rsq_f32_e32 v186, v186
	s_nop 0
	v_mul_f32_e32 v187, 0x45800000, v186
	v_cndmask_b32_e32 v186, v186, v187, vcc
	v_cmp_gt_f32_e32 vcc, s29, v200
	v_mul_f32_e32 v201, 0x4b800000, v200
	s_nop 0
	v_cndmask_b32_e32 v200, v200, v201, vcc
	v_rsq_f32_e32 v200, v200
	s_nop 0
	v_mul_f32_e32 v201, 0x45800000, v200
	v_cndmask_b32_e32 v200, v200, v201, vcc
	v_cmp_gt_f32_e32 vcc, s29, v204
	v_mul_f32_e32 v205, 0x4b800000, v204
	s_nop 0
	v_cndmask_b32_e32 v204, v204, v205, vcc
	v_rsq_f32_e32 v204, v204
	s_nop 0
	v_mul_f32_e32 v205, 0x45800000, v204
	v_cndmask_b32_e32 v204, v204, v205, vcc
	v_cmp_gt_f32_e32 vcc, s29, v208
	v_mul_f32_e32 v209, 0x4b800000, v208
	s_nop 0
	v_cndmask_b32_e32 v208, v208, v209, vcc
	v_rsq_f32_e32 v208, v208
	s_nop 0
	v_mul_f32_e32 v209, 0x45800000, v208
	v_cndmask_b32_e32 v208, v208, v209, vcc
	v_mul_f32_e32 v238, 0xbfb8aa3b, v170
	v_mul_f32_e32 v116, v124, v116
	v_mul_f32_e32 v117, v125, v117
	v_mul_f32_e32 v118, v126, v118
	v_mul_f32_e32 v119, v127, v119
	v_mul_f32_e32 v112, v120, v112
	v_mul_f32_e32 v113, v121, v113
	v_mul_f32_e32 v114, v122, v114
	v_mul_f32_e32 v115, v123, v115
	v_mul_f32_e32 v124, v238, v124
	v_mul_f32_e32 v125, v238, v125
	v_mul_f32_e32 v126, v238, v126
	v_mul_f32_e32 v127, v238, v127
	v_mul_f32_e32 v120, v238, v120
	v_mul_f32_e32 v121, v238, v121
	v_mul_f32_e32 v122, v238, v122
	v_mul_f32_e32 v123, v238, v123
	v_exp_f32_e32 v124, v124
	v_exp_f32_e32 v125, v125
	v_exp_f32_e32 v126, v126
	v_exp_f32_e32 v127, v127
	v_exp_f32_e32 v120, v120
	v_exp_f32_e32 v121, v121
	v_exp_f32_e32 v122, v122
	v_exp_f32_e32 v123, v123
	v_fma_f32 v124, v124, v172, v172
	v_fma_f32 v125, v125, v172, v172
	v_fma_f32 v126, v126, v172, v172
	v_fma_f32 v127, v127, v172, v172
	v_fma_f32 v120, v120, v172, v172
	v_fma_f32 v121, v121, v172, v172
	v_fma_f32 v122, v122, v172, v172
	v_fma_f32 v123, v123, v172, v172
	v_rcp_f32_e32 v124, v124
	v_rcp_f32_e32 v125, v125
	v_rcp_f32_e32 v126, v126
	v_rcp_f32_e32 v127, v127
	v_rcp_f32_e32 v120, v120
	v_rcp_f32_e32 v121, v121
	v_rcp_f32_e32 v122, v122
	v_rcp_f32_e32 v123, v123
	v_add_u32_e32 v242, 0, v150
	v_mad_i64_i32 v[240:241], s[8:9], v242, s72, v[212:213]
	v_mul_f32_e32 v116, v116, v124
	v_mul_f32_e32 v117, v117, v125
	v_mul_f32_e32 v118, v118, v126
	v_mul_f32_e32 v119, v119, v127
	v_mul_f32_e32 v112, v112, v120
	v_mul_f32_e32 v113, v113, v121
	v_mul_f32_e32 v114, v114, v122
	v_mul_f32_e32 v115, v115, v123
	v_lshl_add_u64 v[240:241], v[240:241], 0, v[214:215]
	v_cvt_pk_bf16_f32 v244, v116, v117
	v_cvt_pk_bf16_f32 v245, v118, v119
	v_cvt_pk_bf16_f32 v246, v112, v113
	v_cvt_pk_bf16_f32 v247, v114, v115
	global_store_dwordx4 v[240:241], v[244:247], off sc1
	s_nop 1
	v_mul_f32_e32 v238, 0xbfb8aa3b, v174
	v_mul_f32_e32 v100, v108, v100
	v_mul_f32_e32 v101, v109, v101
	v_mul_f32_e32 v102, v110, v102
	v_mul_f32_e32 v103, v111, v103
	v_mul_f32_e32 v96, v104, v96
	v_mul_f32_e32 v97, v105, v97
	v_mul_f32_e32 v98, v106, v98
	v_mul_f32_e32 v99, v107, v99
	v_mul_f32_e32 v108, v238, v108
	v_mul_f32_e32 v109, v238, v109
	v_mul_f32_e32 v110, v238, v110
	v_mul_f32_e32 v111, v238, v111
	v_mul_f32_e32 v104, v238, v104
	v_mul_f32_e32 v105, v238, v105
	v_mul_f32_e32 v106, v238, v106
	v_mul_f32_e32 v107, v238, v107
	v_exp_f32_e32 v108, v108
	v_exp_f32_e32 v109, v109
	v_exp_f32_e32 v110, v110
	v_exp_f32_e32 v111, v111
	v_exp_f32_e32 v104, v104
	v_exp_f32_e32 v105, v105
	v_exp_f32_e32 v106, v106
	v_exp_f32_e32 v107, v107
	v_fma_f32 v108, v108, v176, v176
	v_fma_f32 v109, v109, v176, v176
	v_fma_f32 v110, v110, v176, v176
	v_fma_f32 v111, v111, v176, v176
	v_fma_f32 v104, v104, v176, v176
	v_fma_f32 v105, v105, v176, v176
	v_fma_f32 v106, v106, v176, v176
	v_fma_f32 v107, v107, v176, v176
	v_rcp_f32_e32 v108, v108
	v_rcp_f32_e32 v109, v109
	v_rcp_f32_e32 v110, v110
	v_rcp_f32_e32 v111, v111
	v_rcp_f32_e32 v104, v104
	v_rcp_f32_e32 v105, v105
	v_rcp_f32_e32 v106, v106
	v_rcp_f32_e32 v107, v107
	v_add_u32_e32 v242, 16, v150
	v_mad_i64_i32 v[240:241], s[8:9], v242, s72, v[212:213]
	v_mul_f32_e32 v100, v100, v108
	v_mul_f32_e32 v101, v101, v109
	v_mul_f32_e32 v102, v102, v110
	v_mul_f32_e32 v103, v103, v111
	v_mul_f32_e32 v96, v96, v104
	v_mul_f32_e32 v97, v97, v105
	v_mul_f32_e32 v98, v98, v106
	v_mul_f32_e32 v99, v99, v107
	v_lshl_add_u64 v[240:241], v[240:241], 0, v[214:215]
	v_cvt_pk_bf16_f32 v244, v100, v101
	v_cvt_pk_bf16_f32 v245, v102, v103
	v_cvt_pk_bf16_f32 v246, v96, v97
	v_cvt_pk_bf16_f32 v247, v98, v99
	global_store_dwordx4 v[240:241], v[244:247], off sc1
	s_nop 1
	v_mul_f32_e32 v238, 0xbfb8aa3b, v178
	v_mul_f32_e32 v84, v92, v84
	v_mul_f32_e32 v85, v93, v85
	v_mul_f32_e32 v86, v94, v86
	v_mul_f32_e32 v87, v95, v87
	v_mul_f32_e32 v80, v88, v80
	v_mul_f32_e32 v81, v89, v81
	v_mul_f32_e32 v82, v90, v82
	v_mul_f32_e32 v83, v91, v83
	v_mul_f32_e32 v92, v238, v92
	v_mul_f32_e32 v93, v238, v93
	v_mul_f32_e32 v94, v238, v94
	v_mul_f32_e32 v95, v238, v95
	v_mul_f32_e32 v88, v238, v88
	v_mul_f32_e32 v89, v238, v89
	v_mul_f32_e32 v90, v238, v90
	v_mul_f32_e32 v91, v238, v91
	v_exp_f32_e32 v92, v92
	v_exp_f32_e32 v93, v93
	v_exp_f32_e32 v94, v94
	v_exp_f32_e32 v95, v95
	v_exp_f32_e32 v88, v88
	v_exp_f32_e32 v89, v89
	v_exp_f32_e32 v90, v90
	v_exp_f32_e32 v91, v91
	v_fma_f32 v92, v92, v180, v180
	v_fma_f32 v93, v93, v180, v180
	v_fma_f32 v94, v94, v180, v180
	v_fma_f32 v95, v95, v180, v180
	v_fma_f32 v88, v88, v180, v180
	v_fma_f32 v89, v89, v180, v180
	v_fma_f32 v90, v90, v180, v180
	v_fma_f32 v91, v91, v180, v180
	v_rcp_f32_e32 v92, v92
	v_rcp_f32_e32 v93, v93
	v_rcp_f32_e32 v94, v94
	v_rcp_f32_e32 v95, v95
	v_rcp_f32_e32 v88, v88
	v_rcp_f32_e32 v89, v89
	v_rcp_f32_e32 v90, v90
	v_rcp_f32_e32 v91, v91
	v_add_u32_e32 v242, 32, v150
	v_mad_i64_i32 v[240:241], s[8:9], v242, s72, v[212:213]
	v_mul_f32_e32 v84, v84, v92
	v_mul_f32_e32 v85, v85, v93
	v_mul_f32_e32 v86, v86, v94
	v_mul_f32_e32 v87, v87, v95
	v_mul_f32_e32 v80, v80, v88
	v_mul_f32_e32 v81, v81, v89
	v_mul_f32_e32 v82, v82, v90
	v_mul_f32_e32 v83, v83, v91
	v_lshl_add_u64 v[240:241], v[240:241], 0, v[214:215]
	v_cvt_pk_bf16_f32 v244, v84, v85
	v_cvt_pk_bf16_f32 v245, v86, v87
	v_cvt_pk_bf16_f32 v246, v80, v81
	v_cvt_pk_bf16_f32 v247, v82, v83
	global_store_dwordx4 v[240:241], v[244:247], off sc1
	s_nop 1
	v_mul_f32_e32 v238, 0xbfb8aa3b, v182
	v_mul_f32_e32 v68, v76, v68
	v_mul_f32_e32 v69, v77, v69
	v_mul_f32_e32 v70, v78, v70
	v_mul_f32_e32 v71, v79, v71
	v_mul_f32_e32 v64, v72, v64
	v_mul_f32_e32 v65, v73, v65
	v_mul_f32_e32 v66, v74, v66
	v_mul_f32_e32 v67, v75, v67
	v_mul_f32_e32 v76, v238, v76
	v_mul_f32_e32 v77, v238, v77
	v_mul_f32_e32 v78, v238, v78
	v_mul_f32_e32 v79, v238, v79
	v_mul_f32_e32 v72, v238, v72
	v_mul_f32_e32 v73, v238, v73
	v_mul_f32_e32 v74, v238, v74
	v_mul_f32_e32 v75, v238, v75
	v_exp_f32_e32 v76, v76
	v_exp_f32_e32 v77, v77
	v_exp_f32_e32 v78, v78
	v_exp_f32_e32 v79, v79
	v_exp_f32_e32 v72, v72
	v_exp_f32_e32 v73, v73
	v_exp_f32_e32 v74, v74
	v_exp_f32_e32 v75, v75
	v_fma_f32 v76, v76, v184, v184
	v_fma_f32 v77, v77, v184, v184
	v_fma_f32 v78, v78, v184, v184
	v_fma_f32 v79, v79, v184, v184
	v_fma_f32 v72, v72, v184, v184
	v_fma_f32 v73, v73, v184, v184
	v_fma_f32 v74, v74, v184, v184
	v_fma_f32 v75, v75, v184, v184
	v_rcp_f32_e32 v76, v76
	v_rcp_f32_e32 v77, v77
	v_rcp_f32_e32 v78, v78
	v_rcp_f32_e32 v79, v79
	v_rcp_f32_e32 v72, v72
	v_rcp_f32_e32 v73, v73
	v_rcp_f32_e32 v74, v74
	v_rcp_f32_e32 v75, v75
	v_add_u32_e32 v242, 48, v150
	v_mad_i64_i32 v[240:241], s[8:9], v242, s72, v[212:213]
	v_mul_f32_e32 v68, v68, v76
	v_mul_f32_e32 v69, v69, v77
	v_mul_f32_e32 v70, v70, v78
	v_mul_f32_e32 v71, v71, v79
	v_mul_f32_e32 v64, v64, v72
	v_mul_f32_e32 v65, v65, v73
	v_mul_f32_e32 v66, v66, v74
	v_mul_f32_e32 v67, v67, v75
	v_lshl_add_u64 v[240:241], v[240:241], 0, v[214:215]
	v_cvt_pk_bf16_f32 v244, v68, v69
	v_cvt_pk_bf16_f32 v245, v70, v71
	v_cvt_pk_bf16_f32 v246, v64, v65
	v_cvt_pk_bf16_f32 v247, v66, v67
	global_store_dwordx4 v[240:241], v[244:247], off sc1
	s_nop 1
	v_mul_f32_e32 v238, 0xbfb8aa3b, v186
	v_mul_f32_e32 v52, v60, v52
	v_mul_f32_e32 v53, v61, v53
	v_mul_f32_e32 v54, v62, v54
	v_mul_f32_e32 v55, v63, v55
	v_mul_f32_e32 v48, v56, v48
	v_mul_f32_e32 v49, v57, v49
	v_mul_f32_e32 v50, v58, v50
	v_mul_f32_e32 v51, v59, v51
	v_mul_f32_e32 v60, v238, v60
	v_mul_f32_e32 v61, v238, v61
	v_mul_f32_e32 v62, v238, v62
	v_mul_f32_e32 v63, v238, v63
	v_mul_f32_e32 v56, v238, v56
	v_mul_f32_e32 v57, v238, v57
	v_mul_f32_e32 v58, v238, v58
	v_mul_f32_e32 v59, v238, v59
	v_exp_f32_e32 v60, v60
	v_exp_f32_e32 v61, v61
	v_exp_f32_e32 v62, v62
	v_exp_f32_e32 v63, v63
	v_exp_f32_e32 v56, v56
	v_exp_f32_e32 v57, v57
	v_exp_f32_e32 v58, v58
	v_exp_f32_e32 v59, v59
	v_fma_f32 v60, v60, v188, v188
	v_fma_f32 v61, v61, v188, v188
	v_fma_f32 v62, v62, v188, v188
	v_fma_f32 v63, v63, v188, v188
	v_fma_f32 v56, v56, v188, v188
	v_fma_f32 v57, v57, v188, v188
	v_fma_f32 v58, v58, v188, v188
	v_fma_f32 v59, v59, v188, v188
	v_rcp_f32_e32 v60, v60
	v_rcp_f32_e32 v61, v61
	v_rcp_f32_e32 v62, v62
	v_rcp_f32_e32 v63, v63
	v_rcp_f32_e32 v56, v56
	v_rcp_f32_e32 v57, v57
	v_rcp_f32_e32 v58, v58
	v_rcp_f32_e32 v59, v59
	v_add_u32_e32 v242, 0x80, v150
	v_mad_i64_i32 v[240:241], s[8:9], v242, s72, v[212:213]
	v_mul_f32_e32 v52, v52, v60
	v_mul_f32_e32 v53, v53, v61
	v_mul_f32_e32 v54, v54, v62
	v_mul_f32_e32 v55, v55, v63
	v_mul_f32_e32 v48, v48, v56
	v_mul_f32_e32 v49, v49, v57
	v_mul_f32_e32 v50, v50, v58
	v_mul_f32_e32 v51, v51, v59
	v_lshl_add_u64 v[240:241], v[240:241], 0, v[214:215]
	v_cvt_pk_bf16_f32 v244, v52, v53
	v_cvt_pk_bf16_f32 v245, v54, v55
	v_cvt_pk_bf16_f32 v246, v48, v49
	v_cvt_pk_bf16_f32 v247, v50, v51
	global_store_dwordx4 v[240:241], v[244:247], off sc1
	s_nop 1
	v_mul_f32_e32 v238, 0xbfb8aa3b, v200
	v_mul_f32_e32 v36, v44, v36
	v_mul_f32_e32 v37, v45, v37
	v_mul_f32_e32 v38, v46, v38
	v_mul_f32_e32 v39, v47, v39
	v_mul_f32_e32 v32, v40, v32
	v_mul_f32_e32 v33, v41, v33
	v_mul_f32_e32 v34, v42, v34
	v_mul_f32_e32 v35, v43, v35
	v_mul_f32_e32 v44, v238, v44
	v_mul_f32_e32 v45, v238, v45
	v_mul_f32_e32 v46, v238, v46
	v_mul_f32_e32 v47, v238, v47
	v_mul_f32_e32 v40, v238, v40
	v_mul_f32_e32 v41, v238, v41
	v_mul_f32_e32 v42, v238, v42
	v_mul_f32_e32 v43, v238, v43
	v_exp_f32_e32 v44, v44
	v_exp_f32_e32 v45, v45
	v_exp_f32_e32 v46, v46
	v_exp_f32_e32 v47, v47
	v_exp_f32_e32 v40, v40
	v_exp_f32_e32 v41, v41
	v_exp_f32_e32 v42, v42
	v_exp_f32_e32 v43, v43
	v_fma_f32 v44, v44, v202, v202
	v_fma_f32 v45, v45, v202, v202
	v_fma_f32 v46, v46, v202, v202
	v_fma_f32 v47, v47, v202, v202
	v_fma_f32 v40, v40, v202, v202
	v_fma_f32 v41, v41, v202, v202
	v_fma_f32 v42, v42, v202, v202
	v_fma_f32 v43, v43, v202, v202
	v_rcp_f32_e32 v44, v44
	v_rcp_f32_e32 v45, v45
	v_rcp_f32_e32 v46, v46
	v_rcp_f32_e32 v47, v47
	v_rcp_f32_e32 v40, v40
	v_rcp_f32_e32 v41, v41
	v_rcp_f32_e32 v42, v42
	v_rcp_f32_e32 v43, v43
	v_add_u32_e32 v242, 0x90, v150
	v_mad_i64_i32 v[240:241], s[8:9], v242, s72, v[212:213]
	v_mul_f32_e32 v36, v36, v44
	v_mul_f32_e32 v37, v37, v45
	v_mul_f32_e32 v38, v38, v46
	v_mul_f32_e32 v39, v39, v47
	v_mul_f32_e32 v32, v32, v40
	v_mul_f32_e32 v33, v33, v41
	v_mul_f32_e32 v34, v34, v42
	v_mul_f32_e32 v35, v35, v43
	v_lshl_add_u64 v[240:241], v[240:241], 0, v[214:215]
	v_cvt_pk_bf16_f32 v244, v36, v37
	v_cvt_pk_bf16_f32 v245, v38, v39
	v_cvt_pk_bf16_f32 v246, v32, v33
	v_cvt_pk_bf16_f32 v247, v34, v35
	global_store_dwordx4 v[240:241], v[244:247], off sc1
	s_nop 1
	v_mul_f32_e32 v238, 0xbfb8aa3b, v204
	v_mul_f32_e32 v20, v28, v20
	v_mul_f32_e32 v21, v29, v21
	v_mul_f32_e32 v22, v30, v22
	v_mul_f32_e32 v23, v31, v23
	v_mul_f32_e32 v16, v24, v16
	v_mul_f32_e32 v17, v25, v17
	v_mul_f32_e32 v18, v26, v18
	v_mul_f32_e32 v19, v27, v19
	v_mul_f32_e32 v28, v238, v28
	v_mul_f32_e32 v29, v238, v29
	v_mul_f32_e32 v30, v238, v30
	v_mul_f32_e32 v31, v238, v31
	v_mul_f32_e32 v24, v238, v24
	v_mul_f32_e32 v25, v238, v25
	v_mul_f32_e32 v26, v238, v26
	v_mul_f32_e32 v27, v238, v27
	v_exp_f32_e32 v28, v28
	v_exp_f32_e32 v29, v29
	v_exp_f32_e32 v30, v30
	v_exp_f32_e32 v31, v31
	v_exp_f32_e32 v24, v24
	v_exp_f32_e32 v25, v25
	v_exp_f32_e32 v26, v26
	v_exp_f32_e32 v27, v27
	v_fma_f32 v28, v28, v206, v206
	v_fma_f32 v29, v29, v206, v206
	v_fma_f32 v30, v30, v206, v206
	v_fma_f32 v31, v31, v206, v206
	v_fma_f32 v24, v24, v206, v206
	v_fma_f32 v25, v25, v206, v206
	v_fma_f32 v26, v26, v206, v206
	v_fma_f32 v27, v27, v206, v206
	v_rcp_f32_e32 v28, v28
	v_rcp_f32_e32 v29, v29
	v_rcp_f32_e32 v30, v30
	v_rcp_f32_e32 v31, v31
	v_rcp_f32_e32 v24, v24
	v_rcp_f32_e32 v25, v25
	v_rcp_f32_e32 v26, v26
	v_rcp_f32_e32 v27, v27
	v_add_u32_e32 v242, 0xa0, v150
	v_mad_i64_i32 v[240:241], s[8:9], v242, s72, v[212:213]
	v_mul_f32_e32 v20, v20, v28
	v_mul_f32_e32 v21, v21, v29
	v_mul_f32_e32 v22, v22, v30
	v_mul_f32_e32 v23, v23, v31
	v_mul_f32_e32 v16, v16, v24
	v_mul_f32_e32 v17, v17, v25
	v_mul_f32_e32 v18, v18, v26
	v_mul_f32_e32 v19, v19, v27
	v_lshl_add_u64 v[240:241], v[240:241], 0, v[214:215]
	v_cvt_pk_bf16_f32 v244, v20, v21
	v_cvt_pk_bf16_f32 v245, v22, v23
	v_cvt_pk_bf16_f32 v246, v16, v17
	v_cvt_pk_bf16_f32 v247, v18, v19
	global_store_dwordx4 v[240:241], v[244:247], off sc1
	s_nop 1
	v_mul_f32_e32 v238, 0xbfb8aa3b, v208
	v_mul_f32_e32 v4, v12, v4
	v_mul_f32_e32 v5, v13, v5
	v_mul_f32_e32 v6, v14, v6
	v_mul_f32_e32 v7, v15, v7
	v_mul_f32_e32 v0, v8, v0
	v_mul_f32_e32 v1, v9, v1
	v_mul_f32_e32 v2, v10, v2
	v_mul_f32_e32 v3, v11, v3
	v_mul_f32_e32 v12, v238, v12
	v_mul_f32_e32 v13, v238, v13
	v_mul_f32_e32 v14, v238, v14
	v_mul_f32_e32 v15, v238, v15
	v_mul_f32_e32 v8, v238, v8
	v_mul_f32_e32 v9, v238, v9
	v_mul_f32_e32 v10, v238, v10
	v_mul_f32_e32 v11, v238, v11
	v_exp_f32_e32 v12, v12
	v_exp_f32_e32 v13, v13
	v_exp_f32_e32 v14, v14
	v_exp_f32_e32 v15, v15
	v_exp_f32_e32 v8, v8
	v_exp_f32_e32 v9, v9
	v_exp_f32_e32 v10, v10
	v_exp_f32_e32 v11, v11
	v_fma_f32 v12, v12, v210, v210
	v_fma_f32 v13, v13, v210, v210
	v_fma_f32 v14, v14, v210, v210
	v_fma_f32 v15, v15, v210, v210
	v_fma_f32 v8, v8, v210, v210
	v_fma_f32 v9, v9, v210, v210
	v_fma_f32 v10, v10, v210, v210
	v_fma_f32 v11, v11, v210, v210
	v_rcp_f32_e32 v12, v12
	v_rcp_f32_e32 v13, v13
	v_rcp_f32_e32 v14, v14
	v_rcp_f32_e32 v15, v15
	v_rcp_f32_e32 v8, v8
	v_rcp_f32_e32 v9, v9
	v_rcp_f32_e32 v10, v10
	v_rcp_f32_e32 v11, v11
	v_add_u32_e32 v242, 0xb0, v150
	v_mad_i64_i32 v[240:241], s[8:9], v242, s72, v[212:213]
	v_mul_f32_e32 v4, v4, v12
	v_mul_f32_e32 v5, v5, v13
	v_mul_f32_e32 v6, v6, v14
	v_mul_f32_e32 v7, v7, v15
	v_mul_f32_e32 v0, v0, v8
	v_mul_f32_e32 v1, v1, v9
	v_mul_f32_e32 v2, v2, v10
	v_mul_f32_e32 v3, v3, v11
	v_lshl_add_u64 v[240:241], v[240:241], 0, v[214:215]
	v_cvt_pk_bf16_f32 v244, v4, v5
	v_cvt_pk_bf16_f32 v245, v6, v7
	v_cvt_pk_bf16_f32 v246, v0, v1
	v_cvt_pk_bf16_f32 v247, v2, v3
	global_store_dwordx4 v[240:241], v[244:247], off sc1
	s_andn2_b64 vcc, exec, s[38:39]
	s_mov_b64 s[8:9], -1
	s_cbranch_vccnz .LBB0_474
